# v8 + pool_stats phase hand rewrite: 8 consecutive tokens per wave, rows streamed once, DPP wave sums (bit-identical math)
# baseline (speedup 1.0000x reference)
.LBB0_788:
	s_lshl_b32 s21, s20, 3
	v_lshlrev_b32_e32 v192, 4, v248
	v_mul_u32_u24_e32 v193, 12, v248
	v_lshlrev_b32_e32 v194, 3, v248
	s_add_u32 s22, s10, 0xc200000
	s_addc_u32 s23, s11, 0
	v_cmp_lt_u32_e64 s[4:5], 15, v248
	v_cmp_lt_u32_e64 s[6:7], 31, v248
	v_cmp_lt_u32_e64 s[8:9], 47, v248
	v_lshrrev_b32_e32 v195, 4, v248
	v_lshlrev_b32_e64 v195, v195, 2
	v_cndmask_b32_e64 v98, 0, 1.0, s[4:5]
	v_cndmask_b32_e64 v99, 0, 1.0, s[6:7]
	v_cndmask_b32_e64 v196, 0, 1.0, s[8:9]
.LPS_LOOP:
	s_lshl_b32 s12, s24, 3
	s_mul_i32 s13, s12, 0xa00
	s_add_u32 s14, s22, s13
	s_addc_u32 s15, s23, 0

	global_load_dwordx3 v[0:2], v193, s[14:15] offset:1024
	global_load_dwordx2 v[32:33], v194, s[14:15] offset:1792
	s_add_u32 s14, s14, 0xa00
	s_addc_u32 s15, s15, 0
	global_load_dwordx3 v[4:6], v193, s[14:15] offset:1024
	global_load_dwordx2 v[34:35], v194, s[14:15] offset:1792
	s_add_u32 s14, s14, 0xa00
	s_addc_u32 s15, s15, 0
	global_load_dwordx3 v[8:10], v193, s[14:15] offset:1024
	global_load_dwordx2 v[36:37], v194, s[14:15] offset:1792
	s_add_u32 s14, s14, 0xa00
	s_addc_u32 s15, s15, 0
	global_load_dwordx3 v[12:14], v193, s[14:15] offset:1024
	global_load_dwordx2 v[38:39], v194, s[14:15] offset:1792
	s_add_u32 s14, s14, 0xa00
	s_addc_u32 s15, s15, 0
	global_load_dwordx3 v[16:18], v193, s[14:15] offset:1024
	global_load_dwordx2 v[40:41], v194, s[14:15] offset:1792
	s_add_u32 s14, s14, 0xa00
	s_addc_u32 s15, s15, 0
	global_load_dwordx3 v[20:22], v193, s[14:15] offset:1024
	global_load_dwordx2 v[42:43], v194, s[14:15] offset:1792
	s_add_u32 s14, s14, 0xa00
	s_addc_u32 s15, s15, 0
	global_load_dwordx3 v[24:26], v193, s[14:15] offset:1024
	global_load_dwordx2 v[44:45], v194, s[14:15] offset:1792
	s_add_u32 s14, s14, 0xa00
	s_addc_u32 s15, s15, 0
	global_load_dwordx3 v[28:30], v193, s[14:15] offset:1024
	global_load_dwordx2 v[46:47], v194, s[14:15] offset:1792
	s_add_i32 s16, s12, 7
	s_mul_i32 s16, s16, 0xa00
	s_add_u32 s18, s22, s16
	s_addc_u32 s19, s23, 0
	global_load_dwordx4 v[100:103], v192, s[18:19]
	s_add_i32 s16, s12, 6
	s_mul_i32 s16, s16, 0xa00
	s_add_u32 s18, s22, s16
	s_addc_u32 s19, s23, 0
	global_load_dwordx4 v[104:107], v192, s[18:19]
	s_add_i32 s16, s12, 5
	s_mul_i32 s16, s16, 0xa00
	s_add_u32 s18, s22, s16
	s_addc_u32 s19, s23, 0
	global_load_dwordx4 v[108:111], v192, s[18:19]
	s_add_i32 s16, s12, 4
	s_mul_i32 s16, s16, 0xa00
	s_add_u32 s18, s22, s16
	s_addc_u32 s19, s23, 0
	global_load_dwordx4 v[112:115], v192, s[18:19]
	s_add_i32 s16, s12, 3
	s_mul_i32 s16, s16, 0xa00
	s_add_u32 s18, s22, s16
	s_addc_u32 s19, s23, 0
	global_load_dwordx4 v[116:119], v192, s[18:19]
	s_add_i32 s16, s12, 2
	s_mul_i32 s16, s16, 0xa00
	s_add_u32 s18, s22, s16
	s_addc_u32 s19, s23, 0
	global_load_dwordx4 v[120:123], v192, s[18:19]
	s_add_i32 s16, s12, 1
	s_mul_i32 s16, s16, 0xa00
	s_add_u32 s18, s22, s16
	s_addc_u32 s19, s23, 0
	global_load_dwordx4 v[124:127], v192, s[18:19]
	s_add_i32 s16, s12, 0
	s_mul_i32 s16, s16, 0xa00
	s_add_u32 s18, s22, s16
	s_addc_u32 s19, s23, 0
	global_load_dwordx4 v[128:131], v192, s[18:19]
	s_add_i32 s16, s12, -1
	s_max_i32 s16, s16, 0
	s_mul_i32 s16, s16, 0xa00
	s_add_u32 s18, s22, s16
	s_addc_u32 s19, s23, 0
	global_load_dwordx4 v[132:135], v192, s[18:19]
	s_add_i32 s16, s12, -2
	s_max_i32 s16, s16, 0
	s_mul_i32 s16, s16, 0xa00
	s_add_u32 s18, s22, s16
	s_addc_u32 s19, s23, 0
	global_load_dwordx4 v[136:139], v192, s[18:19]
	s_add_i32 s16, s12, -3
	s_max_i32 s16, s16, 0
	s_mul_i32 s16, s16, 0xa00
	s_add_u32 s18, s22, s16
	s_addc_u32 s19, s23, 0
	global_load_dwordx4 v[140:143], v192, s[18:19]
	s_add_i32 s16, s12, -4
	s_max_i32 s16, s16, 0
	s_mul_i32 s16, s16, 0xa00
	s_add_u32 s18, s22, s16
	s_addc_u32 s19, s23, 0
	global_load_dwordx4 v[144:147], v192, s[18:19]
	s_add_i32 s16, s12, -5
	s_max_i32 s16, s16, 0
	s_mul_i32 s16, s16, 0xa00
	s_add_u32 s18, s22, s16
	s_addc_u32 s19, s23, 0
	global_load_dwordx4 v[148:151], v192, s[18:19]
	s_add_i32 s16, s12, -6
	s_max_i32 s16, s16, 0
	s_mul_i32 s16, s16, 0xa00
	s_add_u32 s18, s22, s16
	s_addc_u32 s19, s23, 0
	global_load_dwordx4 v[152:155], v192, s[18:19]
	s_add_i32 s16, s12, -7
	s_max_i32 s16, s16, 0
	s_mul_i32 s16, s16, 0xa00
	s_add_u32 s18, s22, s16
	s_addc_u32 s19, s23, 0
	global_load_dwordx4 v[156:159], v192, s[18:19]
	s_add_i32 s16, s12, -8
	s_max_i32 s16, s16, 0
	s_mul_i32 s16, s16, 0xa00
	s_add_u32 s18, s22, s16
	s_addc_u32 s19, s23, 0
	global_load_dwordx4 v[160:163], v192, s[18:19]
	s_add_i32 s16, s12, -9
	s_max_i32 s16, s16, 0
	s_mul_i32 s16, s16, 0xa00
	s_add_u32 s18, s22, s16
	s_addc_u32 s19, s23, 0
	global_load_dwordx4 v[164:167], v192, s[18:19]
	s_add_i32 s16, s12, -10
	s_max_i32 s16, s16, 0
	s_mul_i32 s16, s16, 0xa00
	s_add_u32 s18, s22, s16
	s_addc_u32 s19, s23, 0
	global_load_dwordx4 v[168:171], v192, s[18:19]
	s_add_i32 s16, s12, -11
	s_max_i32 s16, s16, 0
	s_mul_i32 s16, s16, 0xa00
	s_add_u32 s18, s22, s16
	s_addc_u32 s19, s23, 0
	global_load_dwordx4 v[172:175], v192, s[18:19]
	s_add_i32 s16, s12, -12
	s_max_i32 s16, s16, 0
	s_mul_i32 s16, s16, 0xa00
	s_add_u32 s18, s22, s16
	s_addc_u32 s19, s23, 0
	global_load_dwordx4 v[176:179], v192, s[18:19]
	s_add_i32 s16, s12, -13
	s_max_i32 s16, s16, 0
	s_mul_i32 s16, s16, 0xa00
	s_add_u32 s18, s22, s16
	s_addc_u32 s19, s23, 0
	global_load_dwordx4 v[180:183], v192, s[18:19]
	s_add_i32 s16, s12, -14
	s_max_i32 s16, s16, 0
	s_mul_i32 s16, s16, 0xa00
	s_add_u32 s18, s22, s16
	s_addc_u32 s19, s23, 0
	global_load_dwordx4 v[184:187], v192, s[18:19]
	s_add_i32 s16, s12, -15
	s_max_i32 s16, s16, 0
	s_mul_i32 s16, s16, 0xa00
	s_add_u32 s18, s22, s16
	s_addc_u32 s19, s23, 0
	global_load_dwordx4 v[188:191], v192, s[18:19]
	s_movk_i32 s13, 0x4000
	v_min_i32_e32 v81, s13, v195
	v_cvt_f32_i32_e32 v81, v81
	v_div_scale_f32 v82, s[26:27], v81, v81, 1.0
	v_rcp_f32_e32 v85, v82
	s_nop 0
	v_fma_f32 v83, -v82, v85, 1.0
	v_fmac_f32_e32 v85, v83, v85
	v_div_scale_f32 v83, vcc, 1.0, v81, 1.0
	v_mul_f32_e32 v86, v83, v85
	v_fma_f32 v84, -v82, v86, v83
	v_fmac_f32_e32 v86, v84, v85
	v_fma_f32 v83, -v82, v86, v83
	v_div_fmas_f32 v83, v83, v85, v86
	v_div_fixup_f32 v80, v83, v81, 1.0

	s_waitcnt vmcnt(23)
	v_lshlrev_b32_e32 v88, 16, v0
	v_and_b32_e32 v64, 0xffff0000, v0
	v_lshlrev_b32_e32 v89, 16, v32
	v_and_b32_e32 v65, 0xffff0000, v32
	v_mul_f32_e32 v64, v64, v64
	v_mul_f32_e32 v65, v65, v65
	v_fmac_f32_e32 v64, v88, v88
	v_fmac_f32_e32 v65, v89, v89
	v_lshlrev_b32_e32 v88, 16, v1
	v_lshlrev_b32_e32 v89, 16, v33
	v_fmac_f32_e32 v64, v88, v88
	v_fmac_f32_e32 v65, v89, v89
	v_and_b32_e32 v88, 0xffff0000, v1
	v_and_b32_e32 v89, 0xffff0000, v33
	v_fmac_f32_e32 v64, v88, v88
	v_fmac_f32_e32 v65, v89, v89
	v_lshlrev_b32_e32 v88, 16, v2
	v_and_b32_e32 v89, 0xffff0000, v2
	v_fmac_f32_e32 v64, v88, v88
	v_fmac_f32_e32 v64, v89, v89

	v_lshlrev_b32_e32 v88, 16, v4
	v_and_b32_e32 v66, 0xffff0000, v4
	v_lshlrev_b32_e32 v89, 16, v34
	v_and_b32_e32 v67, 0xffff0000, v34
	v_mul_f32_e32 v66, v66, v66
	v_mul_f32_e32 v67, v67, v67
	v_fmac_f32_e32 v66, v88, v88
	v_fmac_f32_e32 v67, v89, v89
	v_lshlrev_b32_e32 v88, 16, v5
	v_lshlrev_b32_e32 v89, 16, v35
	v_fmac_f32_e32 v66, v88, v88
	v_fmac_f32_e32 v67, v89, v89
	v_and_b32_e32 v88, 0xffff0000, v5
	v_and_b32_e32 v89, 0xffff0000, v35
	v_fmac_f32_e32 v66, v88, v88
	v_fmac_f32_e32 v67, v89, v89
	v_lshlrev_b32_e32 v88, 16, v6
	v_and_b32_e32 v89, 0xffff0000, v6
	v_fmac_f32_e32 v66, v88, v88
	v_fmac_f32_e32 v66, v89, v89

	v_lshlrev_b32_e32 v88, 16, v8
	v_and_b32_e32 v68, 0xffff0000, v8
	v_lshlrev_b32_e32 v89, 16, v36
	v_and_b32_e32 v69, 0xffff0000, v36
	v_mul_f32_e32 v68, v68, v68
	v_mul_f32_e32 v69, v69, v69
	v_fmac_f32_e32 v68, v88, v88
	v_fmac_f32_e32 v69, v89, v89
	v_lshlrev_b32_e32 v88, 16, v9
	v_lshlrev_b32_e32 v89, 16, v37
	v_fmac_f32_e32 v68, v88, v88
	v_fmac_f32_e32 v69, v89, v89
	v_and_b32_e32 v88, 0xffff0000, v9
	v_and_b32_e32 v89, 0xffff0000, v37
	v_fmac_f32_e32 v68, v88, v88
	v_fmac_f32_e32 v69, v89, v89
	v_lshlrev_b32_e32 v88, 16, v10
	v_and_b32_e32 v89, 0xffff0000, v10
	v_fmac_f32_e32 v68, v88, v88
	v_fmac_f32_e32 v68, v89, v89

	v_lshlrev_b32_e32 v88, 16, v12
	v_and_b32_e32 v70, 0xffff0000, v12
	v_lshlrev_b32_e32 v89, 16, v38
	v_and_b32_e32 v71, 0xffff0000, v38
	v_mul_f32_e32 v70, v70, v70
	v_mul_f32_e32 v71, v71, v71
	v_fmac_f32_e32 v70, v88, v88
	v_fmac_f32_e32 v71, v89, v89
	v_lshlrev_b32_e32 v88, 16, v13
	v_lshlrev_b32_e32 v89, 16, v39
	v_fmac_f32_e32 v70, v88, v88
	v_fmac_f32_e32 v71, v89, v89
	v_and_b32_e32 v88, 0xffff0000, v13
	v_and_b32_e32 v89, 0xffff0000, v39
	v_fmac_f32_e32 v70, v88, v88
	v_fmac_f32_e32 v71, v89, v89
	v_lshlrev_b32_e32 v88, 16, v14
	v_and_b32_e32 v89, 0xffff0000, v14
	v_fmac_f32_e32 v70, v88, v88
	v_fmac_f32_e32 v70, v89, v89

	v_lshlrev_b32_e32 v88, 16, v16
	v_and_b32_e32 v72, 0xffff0000, v16
	v_lshlrev_b32_e32 v89, 16, v40
	v_and_b32_e32 v73, 0xffff0000, v40
	v_mul_f32_e32 v72, v72, v72
	v_mul_f32_e32 v73, v73, v73
	v_fmac_f32_e32 v72, v88, v88
	v_fmac_f32_e32 v73, v89, v89
	v_lshlrev_b32_e32 v88, 16, v17
	v_lshlrev_b32_e32 v89, 16, v41
	v_fmac_f32_e32 v72, v88, v88
	v_fmac_f32_e32 v73, v89, v89
	v_and_b32_e32 v88, 0xffff0000, v17
	v_and_b32_e32 v89, 0xffff0000, v41
	v_fmac_f32_e32 v72, v88, v88
	v_fmac_f32_e32 v73, v89, v89
	v_lshlrev_b32_e32 v88, 16, v18
	v_and_b32_e32 v89, 0xffff0000, v18
	v_fmac_f32_e32 v72, v88, v88
	v_fmac_f32_e32 v72, v89, v89

	v_lshlrev_b32_e32 v88, 16, v20
	v_and_b32_e32 v74, 0xffff0000, v20
	v_lshlrev_b32_e32 v89, 16, v42
	v_and_b32_e32 v75, 0xffff0000, v42
	v_mul_f32_e32 v74, v74, v74
	v_mul_f32_e32 v75, v75, v75
	v_fmac_f32_e32 v74, v88, v88
	v_fmac_f32_e32 v75, v89, v89
	v_lshlrev_b32_e32 v88, 16, v21
	v_lshlrev_b32_e32 v89, 16, v43
	v_fmac_f32_e32 v74, v88, v88
	v_fmac_f32_e32 v75, v89, v89
	v_and_b32_e32 v88, 0xffff0000, v21
	v_and_b32_e32 v89, 0xffff0000, v43
	v_fmac_f32_e32 v74, v88, v88
	v_fmac_f32_e32 v75, v89, v89
	v_lshlrev_b32_e32 v88, 16, v22
	v_and_b32_e32 v89, 0xffff0000, v22
	v_fmac_f32_e32 v74, v88, v88
	v_fmac_f32_e32 v74, v89, v89

	v_lshlrev_b32_e32 v88, 16, v24
	v_and_b32_e32 v76, 0xffff0000, v24
	v_lshlrev_b32_e32 v89, 16, v44
	v_and_b32_e32 v77, 0xffff0000, v44
	v_mul_f32_e32 v76, v76, v76
	v_mul_f32_e32 v77, v77, v77
	v_fmac_f32_e32 v76, v88, v88
	v_fmac_f32_e32 v77, v89, v89
	v_lshlrev_b32_e32 v88, 16, v25
	v_lshlrev_b32_e32 v89, 16, v45
	v_fmac_f32_e32 v76, v88, v88
	v_fmac_f32_e32 v77, v89, v89
	v_and_b32_e32 v88, 0xffff0000, v25
	v_and_b32_e32 v89, 0xffff0000, v45
	v_fmac_f32_e32 v76, v88, v88
	v_fmac_f32_e32 v77, v89, v89
	v_lshlrev_b32_e32 v88, 16, v26
	v_and_b32_e32 v89, 0xffff0000, v26
	v_fmac_f32_e32 v76, v88, v88
	v_fmac_f32_e32 v76, v89, v89

	v_lshlrev_b32_e32 v88, 16, v28
	v_and_b32_e32 v78, 0xffff0000, v28
	v_lshlrev_b32_e32 v89, 16, v46
	v_and_b32_e32 v79, 0xffff0000, v46
	v_mul_f32_e32 v78, v78, v78
	v_mul_f32_e32 v79, v79, v79
	v_fmac_f32_e32 v78, v88, v88
	v_fmac_f32_e32 v79, v89, v89
	v_lshlrev_b32_e32 v88, 16, v29
	v_lshlrev_b32_e32 v89, 16, v47
	v_fmac_f32_e32 v78, v88, v88
	v_fmac_f32_e32 v79, v89, v89
	v_and_b32_e32 v88, 0xffff0000, v29
	v_and_b32_e32 v89, 0xffff0000, v47
	v_fmac_f32_e32 v78, v88, v88
	v_fmac_f32_e32 v79, v89, v89
	v_lshlrev_b32_e32 v88, 16, v30
	v_and_b32_e32 v89, 0xffff0000, v30
	v_fmac_f32_e32 v78, v88, v88
	v_fmac_f32_e32 v78, v89, v89

	v_add_f32_dpp v64, v64, v64 quad_perm:[1,0,3,2] row_mask:0xf bank_mask:0xf
	v_add_f32_dpp v65, v65, v65 quad_perm:[1,0,3,2] row_mask:0xf bank_mask:0xf
	v_add_f32_dpp v66, v66, v66 quad_perm:[1,0,3,2] row_mask:0xf bank_mask:0xf
	v_add_f32_dpp v67, v67, v67 quad_perm:[1,0,3,2] row_mask:0xf bank_mask:0xf
	v_add_f32_dpp v68, v68, v68 quad_perm:[1,0,3,2] row_mask:0xf bank_mask:0xf
	v_add_f32_dpp v69, v69, v69 quad_perm:[1,0,3,2] row_mask:0xf bank_mask:0xf
	v_add_f32_dpp v70, v70, v70 quad_perm:[1,0,3,2] row_mask:0xf bank_mask:0xf
	v_add_f32_dpp v71, v71, v71 quad_perm:[1,0,3,2] row_mask:0xf bank_mask:0xf
	v_add_f32_dpp v72, v72, v72 quad_perm:[1,0,3,2] row_mask:0xf bank_mask:0xf
	v_add_f32_dpp v73, v73, v73 quad_perm:[1,0,3,2] row_mask:0xf bank_mask:0xf
	v_add_f32_dpp v74, v74, v74 quad_perm:[1,0,3,2] row_mask:0xf bank_mask:0xf
	v_add_f32_dpp v75, v75, v75 quad_perm:[1,0,3,2] row_mask:0xf bank_mask:0xf
	v_add_f32_dpp v76, v76, v76 quad_perm:[1,0,3,2] row_mask:0xf bank_mask:0xf
	v_add_f32_dpp v77, v77, v77 quad_perm:[1,0,3,2] row_mask:0xf bank_mask:0xf
	v_add_f32_dpp v78, v78, v78 quad_perm:[1,0,3,2] row_mask:0xf bank_mask:0xf
	v_add_f32_dpp v79, v79, v79 quad_perm:[1,0,3,2] row_mask:0xf bank_mask:0xf
	v_add_f32_dpp v64, v64, v64 quad_perm:[2,3,0,1] row_mask:0xf bank_mask:0xf
	v_add_f32_dpp v65, v65, v65 quad_perm:[2,3,0,1] row_mask:0xf bank_mask:0xf
	v_add_f32_dpp v66, v66, v66 quad_perm:[2,3,0,1] row_mask:0xf bank_mask:0xf
	v_add_f32_dpp v67, v67, v67 quad_perm:[2,3,0,1] row_mask:0xf bank_mask:0xf
	v_add_f32_dpp v68, v68, v68 quad_perm:[2,3,0,1] row_mask:0xf bank_mask:0xf
	v_add_f32_dpp v69, v69, v69 quad_perm:[2,3,0,1] row_mask:0xf bank_mask:0xf
	v_add_f32_dpp v70, v70, v70 quad_perm:[2,3,0,1] row_mask:0xf bank_mask:0xf
	v_add_f32_dpp v71, v71, v71 quad_perm:[2,3,0,1] row_mask:0xf bank_mask:0xf
	v_add_f32_dpp v72, v72, v72 quad_perm:[2,3,0,1] row_mask:0xf bank_mask:0xf
	v_add_f32_dpp v73, v73, v73 quad_perm:[2,3,0,1] row_mask:0xf bank_mask:0xf
	v_add_f32_dpp v74, v74, v74 quad_perm:[2,3,0,1] row_mask:0xf bank_mask:0xf
	v_add_f32_dpp v75, v75, v75 quad_perm:[2,3,0,1] row_mask:0xf bank_mask:0xf
	v_add_f32_dpp v76, v76, v76 quad_perm:[2,3,0,1] row_mask:0xf bank_mask:0xf
	v_add_f32_dpp v77, v77, v77 quad_perm:[2,3,0,1] row_mask:0xf bank_mask:0xf
	v_add_f32_dpp v78, v78, v78 quad_perm:[2,3,0,1] row_mask:0xf bank_mask:0xf
	v_add_f32_dpp v79, v79, v79 quad_perm:[2,3,0,1] row_mask:0xf bank_mask:0xf
	v_add_f32_dpp v64, v64, v64 row_half_mirror row_mask:0xf bank_mask:0xf
	v_add_f32_dpp v65, v65, v65 row_half_mirror row_mask:0xf bank_mask:0xf
	v_add_f32_dpp v66, v66, v66 row_half_mirror row_mask:0xf bank_mask:0xf
	v_add_f32_dpp v67, v67, v67 row_half_mirror row_mask:0xf bank_mask:0xf
	v_add_f32_dpp v68, v68, v68 row_half_mirror row_mask:0xf bank_mask:0xf
	v_add_f32_dpp v69, v69, v69 row_half_mirror row_mask:0xf bank_mask:0xf
	v_add_f32_dpp v70, v70, v70 row_half_mirror row_mask:0xf bank_mask:0xf
	v_add_f32_dpp v71, v71, v71 row_half_mirror row_mask:0xf bank_mask:0xf
	v_add_f32_dpp v72, v72, v72 row_half_mirror row_mask:0xf bank_mask:0xf
	v_add_f32_dpp v73, v73, v73 row_half_mirror row_mask:0xf bank_mask:0xf
	v_add_f32_dpp v74, v74, v74 row_half_mirror row_mask:0xf bank_mask:0xf
	v_add_f32_dpp v75, v75, v75 row_half_mirror row_mask:0xf bank_mask:0xf
	v_add_f32_dpp v76, v76, v76 row_half_mirror row_mask:0xf bank_mask:0xf
	v_add_f32_dpp v77, v77, v77 row_half_mirror row_mask:0xf bank_mask:0xf
	v_add_f32_dpp v78, v78, v78 row_half_mirror row_mask:0xf bank_mask:0xf
	v_add_f32_dpp v79, v79, v79 row_half_mirror row_mask:0xf bank_mask:0xf
	v_add_f32_dpp v64, v64, v64 row_mirror row_mask:0xf bank_mask:0xf
	v_add_f32_dpp v65, v65, v65 row_mirror row_mask:0xf bank_mask:0xf
	v_add_f32_dpp v66, v66, v66 row_mirror row_mask:0xf bank_mask:0xf
	v_add_f32_dpp v67, v67, v67 row_mirror row_mask:0xf bank_mask:0xf
	v_add_f32_dpp v68, v68, v68 row_mirror row_mask:0xf bank_mask:0xf
	v_add_f32_dpp v69, v69, v69 row_mirror row_mask:0xf bank_mask:0xf
	v_add_f32_dpp v70, v70, v70 row_mirror row_mask:0xf bank_mask:0xf
	v_add_f32_dpp v71, v71, v71 row_mirror row_mask:0xf bank_mask:0xf
	v_add_f32_dpp v72, v72, v72 row_mirror row_mask:0xf bank_mask:0xf
	v_add_f32_dpp v73, v73, v73 row_mirror row_mask:0xf bank_mask:0xf
	v_add_f32_dpp v74, v74, v74 row_mirror row_mask:0xf bank_mask:0xf
	v_add_f32_dpp v75, v75, v75 row_mirror row_mask:0xf bank_mask:0xf
	v_add_f32_dpp v76, v76, v76 row_mirror row_mask:0xf bank_mask:0xf
	v_add_f32_dpp v77, v77, v77 row_mirror row_mask:0xf bank_mask:0xf
	v_add_f32_dpp v78, v78, v78 row_mirror row_mask:0xf bank_mask:0xf
	v_add_f32_dpp v79, v79, v79 row_mirror row_mask:0xf bank_mask:0xf
	v_add_f32_dpp v64, v64, v64 row_bcast:15 row_mask:0xa bank_mask:0xf
	v_add_f32_dpp v65, v65, v65 row_bcast:15 row_mask:0xa bank_mask:0xf
	v_add_f32_dpp v66, v66, v66 row_bcast:15 row_mask:0xa bank_mask:0xf
	v_add_f32_dpp v67, v67, v67 row_bcast:15 row_mask:0xa bank_mask:0xf
	v_add_f32_dpp v68, v68, v68 row_bcast:15 row_mask:0xa bank_mask:0xf
	v_add_f32_dpp v69, v69, v69 row_bcast:15 row_mask:0xa bank_mask:0xf
	v_add_f32_dpp v70, v70, v70 row_bcast:15 row_mask:0xa bank_mask:0xf
	v_add_f32_dpp v71, v71, v71 row_bcast:15 row_mask:0xa bank_mask:0xf
	v_add_f32_dpp v72, v72, v72 row_bcast:15 row_mask:0xa bank_mask:0xf
	v_add_f32_dpp v73, v73, v73 row_bcast:15 row_mask:0xa bank_mask:0xf
	v_add_f32_dpp v74, v74, v74 row_bcast:15 row_mask:0xa bank_mask:0xf
	v_add_f32_dpp v75, v75, v75 row_bcast:15 row_mask:0xa bank_mask:0xf
	v_add_f32_dpp v76, v76, v76 row_bcast:15 row_mask:0xa bank_mask:0xf
	v_add_f32_dpp v77, v77, v77 row_bcast:15 row_mask:0xa bank_mask:0xf
	v_add_f32_dpp v78, v78, v78 row_bcast:15 row_mask:0xa bank_mask:0xf
	v_add_f32_dpp v79, v79, v79 row_bcast:15 row_mask:0xa bank_mask:0xf
	v_add_f32_dpp v64, v64, v64 row_bcast:31 row_mask:0xc bank_mask:0xf
	v_add_f32_dpp v65, v65, v65 row_bcast:31 row_mask:0xc bank_mask:0xf
	v_add_f32_dpp v66, v66, v66 row_bcast:31 row_mask:0xc bank_mask:0xf
	v_add_f32_dpp v67, v67, v67 row_bcast:31 row_mask:0xc bank_mask:0xf
	v_add_f32_dpp v68, v68, v68 row_bcast:31 row_mask:0xc bank_mask:0xf
	v_add_f32_dpp v69, v69, v69 row_bcast:31 row_mask:0xc bank_mask:0xf
	v_add_f32_dpp v70, v70, v70 row_bcast:31 row_mask:0xc bank_mask:0xf
	v_add_f32_dpp v71, v71, v71 row_bcast:31 row_mask:0xc bank_mask:0xf
	v_add_f32_dpp v72, v72, v72 row_bcast:31 row_mask:0xc bank_mask:0xf
	v_add_f32_dpp v73, v73, v73 row_bcast:31 row_mask:0xc bank_mask:0xf
	v_add_f32_dpp v74, v74, v74 row_bcast:31 row_mask:0xc bank_mask:0xf
	v_add_f32_dpp v75, v75, v75 row_bcast:31 row_mask:0xc bank_mask:0xf
	v_add_f32_dpp v76, v76, v76 row_bcast:31 row_mask:0xc bank_mask:0xf
	v_add_f32_dpp v77, v77, v77 row_bcast:31 row_mask:0xc bank_mask:0xf
	v_add_f32_dpp v78, v78, v78 row_bcast:31 row_mask:0xc bank_mask:0xf
	v_add_f32_dpp v79, v79, v79 row_bcast:31 row_mask:0xc bank_mask:0xf
	v_fmamk_f32 v64, v64, 0x3b2aaaab, v249
	v_fmamk_f32 v65, v65, 0x3b800000, v249
	v_fmamk_f32 v66, v66, 0x3b2aaaab, v249
	v_fmamk_f32 v67, v67, 0x3b800000, v249
	v_fmamk_f32 v68, v68, 0x3b2aaaab, v249
	v_fmamk_f32 v69, v69, 0x3b800000, v249
	v_fmamk_f32 v70, v70, 0x3b2aaaab, v249
	v_fmamk_f32 v71, v71, 0x3b800000, v249
	v_fmamk_f32 v72, v72, 0x3b2aaaab, v249
	v_fmamk_f32 v73, v73, 0x3b800000, v249
	v_fmamk_f32 v74, v74, 0x3b2aaaab, v249
	v_fmamk_f32 v75, v75, 0x3b800000, v249
	v_fmamk_f32 v76, v76, 0x3b2aaaab, v249
	v_fmamk_f32 v77, v77, 0x3b800000, v249
	v_fmamk_f32 v78, v78, 0x3b2aaaab, v249
	v_fmamk_f32 v79, v79, 0x3b800000, v249
	v_rsq_f32_e32 v64, v64
	v_rsq_f32_e32 v65, v65
	v_rsq_f32_e32 v66, v66
	v_rsq_f32_e32 v67, v67
	v_rsq_f32_e32 v68, v68
	v_rsq_f32_e32 v69, v69
	v_rsq_f32_e32 v70, v70
	v_rsq_f32_e32 v71, v71
	v_rsq_f32_e32 v72, v72
	v_rsq_f32_e32 v73, v73
	v_rsq_f32_e32 v74, v74
	v_rsq_f32_e32 v75, v75
	v_rsq_f32_e32 v76, v76
	v_rsq_f32_e32 v77, v77
	v_rsq_f32_e32 v78, v78
	v_rsq_f32_e32 v79, v79
	s_waitcnt vmcnt(22)
	v_lshlrev_b32_e32 v88, 16, v100
	v_and_b32_e32 v89, 0xffff0000, v100
	v_lshlrev_b32_e32 v90, 16, v101
	v_and_b32_e32 v91, 0xffff0000, v101
	v_lshlrev_b32_e32 v92, 16, v102
	v_and_b32_e32 v93, 0xffff0000, v102
	v_lshlrev_b32_e32 v94, 16, v103
	v_and_b32_e32 v95, 0xffff0000, v103
	v_fma_f32 v56, 1.0, v88, 0
	v_fma_f32 v57, 1.0, v89, 0
	v_fma_f32 v58, 1.0, v90, 0
	v_fma_f32 v59, 1.0, v91, 0
	v_fma_f32 v60, 1.0, v92, 0
	v_fma_f32 v61, 1.0, v93, 0
	v_fma_f32 v62, 1.0, v94, 0
	v_fma_f32 v63, 1.0, v95, 0
	s_waitcnt vmcnt(21)
	v_lshlrev_b32_e32 v88, 16, v104
	v_and_b32_e32 v89, 0xffff0000, v104
	v_lshlrev_b32_e32 v90, 16, v105
	v_and_b32_e32 v91, 0xffff0000, v105
	v_lshlrev_b32_e32 v92, 16, v106
	v_and_b32_e32 v93, 0xffff0000, v106
	v_lshlrev_b32_e32 v94, 16, v107
	v_and_b32_e32 v95, 0xffff0000, v107
	v_fmac_f32_e32 v56, 1.0, v88
	v_fmac_f32_e32 v57, 1.0, v89
	v_fmac_f32_e32 v58, 1.0, v90
	v_fmac_f32_e32 v59, 1.0, v91
	v_fmac_f32_e32 v60, 1.0, v92
	v_fmac_f32_e32 v61, 1.0, v93
	v_fmac_f32_e32 v62, 1.0, v94
	v_fmac_f32_e32 v63, 1.0, v95
	v_fma_f32 v48, 1.0, v88, 0
	v_fma_f32 v49, 1.0, v89, 0
	v_fma_f32 v50, 1.0, v90, 0
	v_fma_f32 v51, 1.0, v91, 0
	v_fma_f32 v52, 1.0, v92, 0
	v_fma_f32 v53, 1.0, v93, 0
	v_fma_f32 v54, 1.0, v94, 0
	v_fma_f32 v55, 1.0, v95, 0
	s_waitcnt vmcnt(20)
	v_lshlrev_b32_e32 v88, 16, v108
	v_and_b32_e32 v89, 0xffff0000, v108
	v_lshlrev_b32_e32 v90, 16, v109
	v_and_b32_e32 v91, 0xffff0000, v109
	v_lshlrev_b32_e32 v92, 16, v110
	v_and_b32_e32 v93, 0xffff0000, v110
	v_lshlrev_b32_e32 v94, 16, v111
	v_and_b32_e32 v95, 0xffff0000, v111
	v_fmac_f32_e32 v56, v98, v88
	v_fmac_f32_e32 v57, v98, v89
	v_fmac_f32_e32 v58, v98, v90
	v_fmac_f32_e32 v59, v98, v91
	v_fmac_f32_e32 v60, v98, v92
	v_fmac_f32_e32 v61, v98, v93
	v_fmac_f32_e32 v62, v98, v94
	v_fmac_f32_e32 v63, v98, v95
	v_fmac_f32_e32 v48, 1.0, v88
	v_fmac_f32_e32 v49, 1.0, v89
	v_fmac_f32_e32 v50, 1.0, v90
	v_fmac_f32_e32 v51, 1.0, v91
	v_fmac_f32_e32 v52, 1.0, v92
	v_fmac_f32_e32 v53, 1.0, v93
	v_fmac_f32_e32 v54, 1.0, v94
	v_fmac_f32_e32 v55, 1.0, v95
	v_fma_f32 v40, 1.0, v88, 0
	v_fma_f32 v41, 1.0, v89, 0
	v_fma_f32 v42, 1.0, v90, 0
	v_fma_f32 v43, 1.0, v91, 0
	v_fma_f32 v44, 1.0, v92, 0
	v_fma_f32 v45, 1.0, v93, 0
	v_fma_f32 v46, 1.0, v94, 0
	v_fma_f32 v47, 1.0, v95, 0
	s_waitcnt vmcnt(19)
	v_lshlrev_b32_e32 v88, 16, v112
	v_and_b32_e32 v89, 0xffff0000, v112
	v_lshlrev_b32_e32 v90, 16, v113
	v_and_b32_e32 v91, 0xffff0000, v113
	v_lshlrev_b32_e32 v92, 16, v114
	v_and_b32_e32 v93, 0xffff0000, v114
	v_lshlrev_b32_e32 v94, 16, v115
	v_and_b32_e32 v95, 0xffff0000, v115
	v_fmac_f32_e32 v56, v98, v88
	v_fmac_f32_e32 v57, v98, v89
	v_fmac_f32_e32 v58, v98, v90
	v_fmac_f32_e32 v59, v98, v91
	v_fmac_f32_e32 v60, v98, v92
	v_fmac_f32_e32 v61, v98, v93
	v_fmac_f32_e32 v62, v98, v94
	v_fmac_f32_e32 v63, v98, v95
	v_fmac_f32_e32 v48, v98, v88
	v_fmac_f32_e32 v49, v98, v89
	v_fmac_f32_e32 v50, v98, v90
	v_fmac_f32_e32 v51, v98, v91
	v_fmac_f32_e32 v52, v98, v92
	v_fmac_f32_e32 v53, v98, v93
	v_fmac_f32_e32 v54, v98, v94
	v_fmac_f32_e32 v55, v98, v95
	v_fmac_f32_e32 v40, 1.0, v88
	v_fmac_f32_e32 v41, 1.0, v89
	v_fmac_f32_e32 v42, 1.0, v90
	v_fmac_f32_e32 v43, 1.0, v91
	v_fmac_f32_e32 v44, 1.0, v92
	v_fmac_f32_e32 v45, 1.0, v93
	v_fmac_f32_e32 v46, 1.0, v94
	v_fmac_f32_e32 v47, 1.0, v95
	v_fma_f32 v32, 1.0, v88, 0
	v_fma_f32 v33, 1.0, v89, 0
	v_fma_f32 v34, 1.0, v90, 0
	v_fma_f32 v35, 1.0, v91, 0
	v_fma_f32 v36, 1.0, v92, 0
	v_fma_f32 v37, 1.0, v93, 0
	v_fma_f32 v38, 1.0, v94, 0
	v_fma_f32 v39, 1.0, v95, 0
	s_waitcnt vmcnt(18)
	v_lshlrev_b32_e32 v88, 16, v116
	v_and_b32_e32 v89, 0xffff0000, v116
	v_lshlrev_b32_e32 v90, 16, v117
	v_and_b32_e32 v91, 0xffff0000, v117
	v_lshlrev_b32_e32 v92, 16, v118
	v_and_b32_e32 v93, 0xffff0000, v118
	v_lshlrev_b32_e32 v94, 16, v119
	v_and_b32_e32 v95, 0xffff0000, v119
	v_fmac_f32_e32 v56, v99, v88
	v_fmac_f32_e32 v57, v99, v89
	v_fmac_f32_e32 v58, v99, v90
	v_fmac_f32_e32 v59, v99, v91
	v_fmac_f32_e32 v60, v99, v92
	v_fmac_f32_e32 v61, v99, v93
	v_fmac_f32_e32 v62, v99, v94
	v_fmac_f32_e32 v63, v99, v95
	v_fmac_f32_e32 v48, v98, v88
	v_fmac_f32_e32 v49, v98, v89
	v_fmac_f32_e32 v50, v98, v90
	v_fmac_f32_e32 v51, v98, v91
	v_fmac_f32_e32 v52, v98, v92
	v_fmac_f32_e32 v53, v98, v93
	v_fmac_f32_e32 v54, v98, v94
	v_fmac_f32_e32 v55, v98, v95
	v_fmac_f32_e32 v40, v98, v88
	v_fmac_f32_e32 v41, v98, v89
	v_fmac_f32_e32 v42, v98, v90
	v_fmac_f32_e32 v43, v98, v91
	v_fmac_f32_e32 v44, v98, v92
	v_fmac_f32_e32 v45, v98, v93
	v_fmac_f32_e32 v46, v98, v94
	v_fmac_f32_e32 v47, v98, v95
	v_fmac_f32_e32 v32, 1.0, v88
	v_fmac_f32_e32 v33, 1.0, v89
	v_fmac_f32_e32 v34, 1.0, v90
	v_fmac_f32_e32 v35, 1.0, v91
	v_fmac_f32_e32 v36, 1.0, v92
	v_fmac_f32_e32 v37, 1.0, v93
	v_fmac_f32_e32 v38, 1.0, v94
	v_fmac_f32_e32 v39, 1.0, v95
	v_fma_f32 v24, 1.0, v88, 0
	v_fma_f32 v25, 1.0, v89, 0
	v_fma_f32 v26, 1.0, v90, 0
	v_fma_f32 v27, 1.0, v91, 0
	v_fma_f32 v28, 1.0, v92, 0
	v_fma_f32 v29, 1.0, v93, 0
	v_fma_f32 v30, 1.0, v94, 0
	v_fma_f32 v31, 1.0, v95, 0
	s_waitcnt vmcnt(17)
	v_lshlrev_b32_e32 v88, 16, v120
	v_and_b32_e32 v89, 0xffff0000, v120
	v_lshlrev_b32_e32 v90, 16, v121
	v_and_b32_e32 v91, 0xffff0000, v121
	v_lshlrev_b32_e32 v92, 16, v122
	v_and_b32_e32 v93, 0xffff0000, v122
	v_lshlrev_b32_e32 v94, 16, v123
	v_and_b32_e32 v95, 0xffff0000, v123
	v_fmac_f32_e32 v56, v99, v88
	v_fmac_f32_e32 v57, v99, v89
	v_fmac_f32_e32 v58, v99, v90
	v_fmac_f32_e32 v59, v99, v91
	v_fmac_f32_e32 v60, v99, v92
	v_fmac_f32_e32 v61, v99, v93
	v_fmac_f32_e32 v62, v99, v94
	v_fmac_f32_e32 v63, v99, v95
	v_fmac_f32_e32 v48, v99, v88
	v_fmac_f32_e32 v49, v99, v89
	v_fmac_f32_e32 v50, v99, v90
	v_fmac_f32_e32 v51, v99, v91
	v_fmac_f32_e32 v52, v99, v92
	v_fmac_f32_e32 v53, v99, v93
	v_fmac_f32_e32 v54, v99, v94
	v_fmac_f32_e32 v55, v99, v95
	v_fmac_f32_e32 v40, v98, v88
	v_fmac_f32_e32 v41, v98, v89
	v_fmac_f32_e32 v42, v98, v90
	v_fmac_f32_e32 v43, v98, v91
	v_fmac_f32_e32 v44, v98, v92
	v_fmac_f32_e32 v45, v98, v93
	v_fmac_f32_e32 v46, v98, v94
	v_fmac_f32_e32 v47, v98, v95
	v_fmac_f32_e32 v32, v98, v88
	v_fmac_f32_e32 v33, v98, v89
	v_fmac_f32_e32 v34, v98, v90
	v_fmac_f32_e32 v35, v98, v91
	v_fmac_f32_e32 v36, v98, v92
	v_fmac_f32_e32 v37, v98, v93
	v_fmac_f32_e32 v38, v98, v94
	v_fmac_f32_e32 v39, v98, v95
	v_fmac_f32_e32 v24, 1.0, v88
	v_fmac_f32_e32 v25, 1.0, v89
	v_fmac_f32_e32 v26, 1.0, v90
	v_fmac_f32_e32 v27, 1.0, v91
	v_fmac_f32_e32 v28, 1.0, v92
	v_fmac_f32_e32 v29, 1.0, v93
	v_fmac_f32_e32 v30, 1.0, v94
	v_fmac_f32_e32 v31, 1.0, v95
	v_fma_f32 v16, 1.0, v88, 0
	v_fma_f32 v17, 1.0, v89, 0
	v_fma_f32 v18, 1.0, v90, 0
	v_fma_f32 v19, 1.0, v91, 0
	v_fma_f32 v20, 1.0, v92, 0
	v_fma_f32 v21, 1.0, v93, 0
	v_fma_f32 v22, 1.0, v94, 0
	v_fma_f32 v23, 1.0, v95, 0
	s_waitcnt vmcnt(16)
	v_lshlrev_b32_e32 v88, 16, v124
	v_and_b32_e32 v89, 0xffff0000, v124
	v_lshlrev_b32_e32 v90, 16, v125
	v_and_b32_e32 v91, 0xffff0000, v125
	v_lshlrev_b32_e32 v92, 16, v126
	v_and_b32_e32 v93, 0xffff0000, v126
	v_lshlrev_b32_e32 v94, 16, v127
	v_and_b32_e32 v95, 0xffff0000, v127
	v_fmac_f32_e32 v56, v99, v88
	v_fmac_f32_e32 v57, v99, v89
	v_fmac_f32_e32 v58, v99, v90
	v_fmac_f32_e32 v59, v99, v91
	v_fmac_f32_e32 v60, v99, v92
	v_fmac_f32_e32 v61, v99, v93
	v_fmac_f32_e32 v62, v99, v94
	v_fmac_f32_e32 v63, v99, v95
	v_fmac_f32_e32 v48, v99, v88
	v_fmac_f32_e32 v49, v99, v89
	v_fmac_f32_e32 v50, v99, v90
	v_fmac_f32_e32 v51, v99, v91
	v_fmac_f32_e32 v52, v99, v92
	v_fmac_f32_e32 v53, v99, v93
	v_fmac_f32_e32 v54, v99, v94
	v_fmac_f32_e32 v55, v99, v95
	v_fmac_f32_e32 v40, v99, v88
	v_fmac_f32_e32 v41, v99, v89
	v_fmac_f32_e32 v42, v99, v90
	v_fmac_f32_e32 v43, v99, v91
	v_fmac_f32_e32 v44, v99, v92
	v_fmac_f32_e32 v45, v99, v93
	v_fmac_f32_e32 v46, v99, v94
	v_fmac_f32_e32 v47, v99, v95
	v_fmac_f32_e32 v32, v98, v88
	v_fmac_f32_e32 v33, v98, v89
	v_fmac_f32_e32 v34, v98, v90
	v_fmac_f32_e32 v35, v98, v91
	v_fmac_f32_e32 v36, v98, v92
	v_fmac_f32_e32 v37, v98, v93
	v_fmac_f32_e32 v38, v98, v94
	v_fmac_f32_e32 v39, v98, v95
	v_fmac_f32_e32 v24, v98, v88
	v_fmac_f32_e32 v25, v98, v89
	v_fmac_f32_e32 v26, v98, v90
	v_fmac_f32_e32 v27, v98, v91
	v_fmac_f32_e32 v28, v98, v92
	v_fmac_f32_e32 v29, v98, v93
	v_fmac_f32_e32 v30, v98, v94
	v_fmac_f32_e32 v31, v98, v95
	v_fmac_f32_e32 v16, 1.0, v88
	v_fmac_f32_e32 v17, 1.0, v89
	v_fmac_f32_e32 v18, 1.0, v90
	v_fmac_f32_e32 v19, 1.0, v91
	v_fmac_f32_e32 v20, 1.0, v92
	v_fmac_f32_e32 v21, 1.0, v93
	v_fmac_f32_e32 v22, 1.0, v94
	v_fmac_f32_e32 v23, 1.0, v95
	v_fma_f32 v8, 1.0, v88, 0
	v_fma_f32 v9, 1.0, v89, 0
	v_fma_f32 v10, 1.0, v90, 0
	v_fma_f32 v11, 1.0, v91, 0
	v_fma_f32 v12, 1.0, v92, 0
	v_fma_f32 v13, 1.0, v93, 0
	v_fma_f32 v14, 1.0, v94, 0
	v_fma_f32 v15, 1.0, v95, 0
	s_waitcnt vmcnt(15)
	v_lshlrev_b32_e32 v88, 16, v128
	v_and_b32_e32 v89, 0xffff0000, v128
	v_lshlrev_b32_e32 v90, 16, v129
	v_and_b32_e32 v91, 0xffff0000, v129
	v_lshlrev_b32_e32 v92, 16, v130
	v_and_b32_e32 v93, 0xffff0000, v130
	v_lshlrev_b32_e32 v94, 16, v131
	v_and_b32_e32 v95, 0xffff0000, v131
	v_fmac_f32_e32 v56, v99, v88
	v_fmac_f32_e32 v57, v99, v89
	v_fmac_f32_e32 v58, v99, v90
	v_fmac_f32_e32 v59, v99, v91
	v_fmac_f32_e32 v60, v99, v92
	v_fmac_f32_e32 v61, v99, v93
	v_fmac_f32_e32 v62, v99, v94
	v_fmac_f32_e32 v63, v99, v95
	v_fmac_f32_e32 v48, v99, v88
	v_fmac_f32_e32 v49, v99, v89
	v_fmac_f32_e32 v50, v99, v90
	v_fmac_f32_e32 v51, v99, v91
	v_fmac_f32_e32 v52, v99, v92
	v_fmac_f32_e32 v53, v99, v93
	v_fmac_f32_e32 v54, v99, v94
	v_fmac_f32_e32 v55, v99, v95
	v_fmac_f32_e32 v40, v99, v88
	v_fmac_f32_e32 v41, v99, v89
	v_fmac_f32_e32 v42, v99, v90
	v_fmac_f32_e32 v43, v99, v91
	v_fmac_f32_e32 v44, v99, v92
	v_fmac_f32_e32 v45, v99, v93
	v_fmac_f32_e32 v46, v99, v94
	v_fmac_f32_e32 v47, v99, v95
	v_fmac_f32_e32 v32, v99, v88
	v_fmac_f32_e32 v33, v99, v89
	v_fmac_f32_e32 v34, v99, v90
	v_fmac_f32_e32 v35, v99, v91
	v_fmac_f32_e32 v36, v99, v92
	v_fmac_f32_e32 v37, v99, v93
	v_fmac_f32_e32 v38, v99, v94
	v_fmac_f32_e32 v39, v99, v95
	v_fmac_f32_e32 v24, v98, v88
	v_fmac_f32_e32 v25, v98, v89
	v_fmac_f32_e32 v26, v98, v90
	v_fmac_f32_e32 v27, v98, v91
	v_fmac_f32_e32 v28, v98, v92
	v_fmac_f32_e32 v29, v98, v93
	v_fmac_f32_e32 v30, v98, v94
	v_fmac_f32_e32 v31, v98, v95
	v_fmac_f32_e32 v16, v98, v88
	v_fmac_f32_e32 v17, v98, v89
	v_fmac_f32_e32 v18, v98, v90
	v_fmac_f32_e32 v19, v98, v91
	v_fmac_f32_e32 v20, v98, v92
	v_fmac_f32_e32 v21, v98, v93
	v_fmac_f32_e32 v22, v98, v94
	v_fmac_f32_e32 v23, v98, v95
	v_fmac_f32_e32 v8, 1.0, v88
	v_fmac_f32_e32 v9, 1.0, v89
	v_fmac_f32_e32 v10, 1.0, v90
	v_fmac_f32_e32 v11, 1.0, v91
	v_fmac_f32_e32 v12, 1.0, v92
	v_fmac_f32_e32 v13, 1.0, v93
	v_fmac_f32_e32 v14, 1.0, v94
	v_fmac_f32_e32 v15, 1.0, v95
	v_fma_f32 v0, 1.0, v88, 0
	v_fma_f32 v1, 1.0, v89, 0
	v_fma_f32 v2, 1.0, v90, 0
	v_fma_f32 v3, 1.0, v91, 0
	v_fma_f32 v4, 1.0, v92, 0
	v_fma_f32 v5, 1.0, v93, 0
	v_fma_f32 v6, 1.0, v94, 0
	v_fma_f32 v7, 1.0, v95, 0
	s_cmp_eq_u32 s12, 0
	s_cbranch_scc1 .LPS_ROWS_DONE
	s_waitcnt vmcnt(14)
	v_lshlrev_b32_e32 v88, 16, v132
	v_and_b32_e32 v89, 0xffff0000, v132
	v_lshlrev_b32_e32 v90, 16, v133
	v_and_b32_e32 v91, 0xffff0000, v133
	v_lshlrev_b32_e32 v92, 16, v134
	v_and_b32_e32 v93, 0xffff0000, v134
	v_lshlrev_b32_e32 v94, 16, v135
	v_and_b32_e32 v95, 0xffff0000, v135
	v_fmac_f32_e32 v56, v196, v88
	v_fmac_f32_e32 v57, v196, v89
	v_fmac_f32_e32 v58, v196, v90
	v_fmac_f32_e32 v59, v196, v91
	v_fmac_f32_e32 v60, v196, v92
	v_fmac_f32_e32 v61, v196, v93
	v_fmac_f32_e32 v62, v196, v94
	v_fmac_f32_e32 v63, v196, v95
	v_fmac_f32_e32 v48, v99, v88
	v_fmac_f32_e32 v49, v99, v89
	v_fmac_f32_e32 v50, v99, v90
	v_fmac_f32_e32 v51, v99, v91
	v_fmac_f32_e32 v52, v99, v92
	v_fmac_f32_e32 v53, v99, v93
	v_fmac_f32_e32 v54, v99, v94
	v_fmac_f32_e32 v55, v99, v95
	v_fmac_f32_e32 v40, v99, v88
	v_fmac_f32_e32 v41, v99, v89
	v_fmac_f32_e32 v42, v99, v90
	v_fmac_f32_e32 v43, v99, v91
	v_fmac_f32_e32 v44, v99, v92
	v_fmac_f32_e32 v45, v99, v93
	v_fmac_f32_e32 v46, v99, v94
	v_fmac_f32_e32 v47, v99, v95
	v_fmac_f32_e32 v32, v99, v88
	v_fmac_f32_e32 v33, v99, v89
	v_fmac_f32_e32 v34, v99, v90
	v_fmac_f32_e32 v35, v99, v91
	v_fmac_f32_e32 v36, v99, v92
	v_fmac_f32_e32 v37, v99, v93
	v_fmac_f32_e32 v38, v99, v94
	v_fmac_f32_e32 v39, v99, v95
	v_fmac_f32_e32 v24, v99, v88
	v_fmac_f32_e32 v25, v99, v89
	v_fmac_f32_e32 v26, v99, v90
	v_fmac_f32_e32 v27, v99, v91
	v_fmac_f32_e32 v28, v99, v92
	v_fmac_f32_e32 v29, v99, v93
	v_fmac_f32_e32 v30, v99, v94
	v_fmac_f32_e32 v31, v99, v95
	v_fmac_f32_e32 v16, v98, v88
	v_fmac_f32_e32 v17, v98, v89
	v_fmac_f32_e32 v18, v98, v90
	v_fmac_f32_e32 v19, v98, v91
	v_fmac_f32_e32 v20, v98, v92
	v_fmac_f32_e32 v21, v98, v93
	v_fmac_f32_e32 v22, v98, v94
	v_fmac_f32_e32 v23, v98, v95
	v_fmac_f32_e32 v8, v98, v88
	v_fmac_f32_e32 v9, v98, v89
	v_fmac_f32_e32 v10, v98, v90
	v_fmac_f32_e32 v11, v98, v91
	v_fmac_f32_e32 v12, v98, v92
	v_fmac_f32_e32 v13, v98, v93
	v_fmac_f32_e32 v14, v98, v94
	v_fmac_f32_e32 v15, v98, v95
	v_fmac_f32_e32 v0, 1.0, v88
	v_fmac_f32_e32 v1, 1.0, v89
	v_fmac_f32_e32 v2, 1.0, v90
	v_fmac_f32_e32 v3, 1.0, v91
	v_fmac_f32_e32 v4, 1.0, v92
	v_fmac_f32_e32 v5, 1.0, v93
	v_fmac_f32_e32 v6, 1.0, v94
	v_fmac_f32_e32 v7, 1.0, v95
	s_waitcnt vmcnt(13)
	v_lshlrev_b32_e32 v88, 16, v136
	v_and_b32_e32 v89, 0xffff0000, v136
	v_lshlrev_b32_e32 v90, 16, v137
	v_and_b32_e32 v91, 0xffff0000, v137
	v_lshlrev_b32_e32 v92, 16, v138
	v_and_b32_e32 v93, 0xffff0000, v138
	v_lshlrev_b32_e32 v94, 16, v139
	v_and_b32_e32 v95, 0xffff0000, v139
	v_fmac_f32_e32 v56, v196, v88
	v_fmac_f32_e32 v57, v196, v89
	v_fmac_f32_e32 v58, v196, v90
	v_fmac_f32_e32 v59, v196, v91
	v_fmac_f32_e32 v60, v196, v92
	v_fmac_f32_e32 v61, v196, v93
	v_fmac_f32_e32 v62, v196, v94
	v_fmac_f32_e32 v63, v196, v95
	v_fmac_f32_e32 v48, v196, v88
	v_fmac_f32_e32 v49, v196, v89
	v_fmac_f32_e32 v50, v196, v90
	v_fmac_f32_e32 v51, v196, v91
	v_fmac_f32_e32 v52, v196, v92
	v_fmac_f32_e32 v53, v196, v93
	v_fmac_f32_e32 v54, v196, v94
	v_fmac_f32_e32 v55, v196, v95
	v_fmac_f32_e32 v40, v99, v88
	v_fmac_f32_e32 v41, v99, v89
	v_fmac_f32_e32 v42, v99, v90
	v_fmac_f32_e32 v43, v99, v91
	v_fmac_f32_e32 v44, v99, v92
	v_fmac_f32_e32 v45, v99, v93
	v_fmac_f32_e32 v46, v99, v94
	v_fmac_f32_e32 v47, v99, v95
	v_fmac_f32_e32 v32, v99, v88
	v_fmac_f32_e32 v33, v99, v89
	v_fmac_f32_e32 v34, v99, v90
	v_fmac_f32_e32 v35, v99, v91
	v_fmac_f32_e32 v36, v99, v92
	v_fmac_f32_e32 v37, v99, v93
	v_fmac_f32_e32 v38, v99, v94
	v_fmac_f32_e32 v39, v99, v95
	v_fmac_f32_e32 v24, v99, v88
	v_fmac_f32_e32 v25, v99, v89
	v_fmac_f32_e32 v26, v99, v90
	v_fmac_f32_e32 v27, v99, v91
	v_fmac_f32_e32 v28, v99, v92
	v_fmac_f32_e32 v29, v99, v93
	v_fmac_f32_e32 v30, v99, v94
	v_fmac_f32_e32 v31, v99, v95
	v_fmac_f32_e32 v16, v99, v88
	v_fmac_f32_e32 v17, v99, v89
	v_fmac_f32_e32 v18, v99, v90
	v_fmac_f32_e32 v19, v99, v91
	v_fmac_f32_e32 v20, v99, v92
	v_fmac_f32_e32 v21, v99, v93
	v_fmac_f32_e32 v22, v99, v94
	v_fmac_f32_e32 v23, v99, v95
	v_fmac_f32_e32 v8, v98, v88
	v_fmac_f32_e32 v9, v98, v89
	v_fmac_f32_e32 v10, v98, v90
	v_fmac_f32_e32 v11, v98, v91
	v_fmac_f32_e32 v12, v98, v92
	v_fmac_f32_e32 v13, v98, v93
	v_fmac_f32_e32 v14, v98, v94
	v_fmac_f32_e32 v15, v98, v95
	v_fmac_f32_e32 v0, v98, v88
	v_fmac_f32_e32 v1, v98, v89
	v_fmac_f32_e32 v2, v98, v90
	v_fmac_f32_e32 v3, v98, v91
	v_fmac_f32_e32 v4, v98, v92
	v_fmac_f32_e32 v5, v98, v93
	v_fmac_f32_e32 v6, v98, v94
	v_fmac_f32_e32 v7, v98, v95
	s_waitcnt vmcnt(12)
	v_lshlrev_b32_e32 v88, 16, v140
	v_and_b32_e32 v89, 0xffff0000, v140
	v_lshlrev_b32_e32 v90, 16, v141
	v_and_b32_e32 v91, 0xffff0000, v141
	v_lshlrev_b32_e32 v92, 16, v142
	v_and_b32_e32 v93, 0xffff0000, v142
	v_lshlrev_b32_e32 v94, 16, v143
	v_and_b32_e32 v95, 0xffff0000, v143
	v_fmac_f32_e32 v56, v196, v88
	v_fmac_f32_e32 v57, v196, v89
	v_fmac_f32_e32 v58, v196, v90
	v_fmac_f32_e32 v59, v196, v91
	v_fmac_f32_e32 v60, v196, v92
	v_fmac_f32_e32 v61, v196, v93
	v_fmac_f32_e32 v62, v196, v94
	v_fmac_f32_e32 v63, v196, v95
	v_fmac_f32_e32 v48, v196, v88
	v_fmac_f32_e32 v49, v196, v89
	v_fmac_f32_e32 v50, v196, v90
	v_fmac_f32_e32 v51, v196, v91
	v_fmac_f32_e32 v52, v196, v92
	v_fmac_f32_e32 v53, v196, v93
	v_fmac_f32_e32 v54, v196, v94
	v_fmac_f32_e32 v55, v196, v95
	v_fmac_f32_e32 v40, v196, v88
	v_fmac_f32_e32 v41, v196, v89
	v_fmac_f32_e32 v42, v196, v90
	v_fmac_f32_e32 v43, v196, v91
	v_fmac_f32_e32 v44, v196, v92
	v_fmac_f32_e32 v45, v196, v93
	v_fmac_f32_e32 v46, v196, v94
	v_fmac_f32_e32 v47, v196, v95
	v_fmac_f32_e32 v32, v99, v88
	v_fmac_f32_e32 v33, v99, v89
	v_fmac_f32_e32 v34, v99, v90
	v_fmac_f32_e32 v35, v99, v91
	v_fmac_f32_e32 v36, v99, v92
	v_fmac_f32_e32 v37, v99, v93
	v_fmac_f32_e32 v38, v99, v94
	v_fmac_f32_e32 v39, v99, v95
	v_fmac_f32_e32 v24, v99, v88
	v_fmac_f32_e32 v25, v99, v89
	v_fmac_f32_e32 v26, v99, v90
	v_fmac_f32_e32 v27, v99, v91
	v_fmac_f32_e32 v28, v99, v92
	v_fmac_f32_e32 v29, v99, v93
	v_fmac_f32_e32 v30, v99, v94
	v_fmac_f32_e32 v31, v99, v95
	v_fmac_f32_e32 v16, v99, v88
	v_fmac_f32_e32 v17, v99, v89
	v_fmac_f32_e32 v18, v99, v90
	v_fmac_f32_e32 v19, v99, v91
	v_fmac_f32_e32 v20, v99, v92
	v_fmac_f32_e32 v21, v99, v93
	v_fmac_f32_e32 v22, v99, v94
	v_fmac_f32_e32 v23, v99, v95
	v_fmac_f32_e32 v8, v99, v88
	v_fmac_f32_e32 v9, v99, v89
	v_fmac_f32_e32 v10, v99, v90
	v_fmac_f32_e32 v11, v99, v91
	v_fmac_f32_e32 v12, v99, v92
	v_fmac_f32_e32 v13, v99, v93
	v_fmac_f32_e32 v14, v99, v94
	v_fmac_f32_e32 v15, v99, v95
	v_fmac_f32_e32 v0, v98, v88
	v_fmac_f32_e32 v1, v98, v89
	v_fmac_f32_e32 v2, v98, v90
	v_fmac_f32_e32 v3, v98, v91
	v_fmac_f32_e32 v4, v98, v92
	v_fmac_f32_e32 v5, v98, v93
	v_fmac_f32_e32 v6, v98, v94
	v_fmac_f32_e32 v7, v98, v95
	s_waitcnt vmcnt(11)
	v_lshlrev_b32_e32 v88, 16, v144
	v_and_b32_e32 v89, 0xffff0000, v144
	v_lshlrev_b32_e32 v90, 16, v145
	v_and_b32_e32 v91, 0xffff0000, v145
	v_lshlrev_b32_e32 v92, 16, v146
	v_and_b32_e32 v93, 0xffff0000, v146
	v_lshlrev_b32_e32 v94, 16, v147
	v_and_b32_e32 v95, 0xffff0000, v147
	v_fmac_f32_e32 v56, v196, v88
	v_fmac_f32_e32 v57, v196, v89
	v_fmac_f32_e32 v58, v196, v90
	v_fmac_f32_e32 v59, v196, v91
	v_fmac_f32_e32 v60, v196, v92
	v_fmac_f32_e32 v61, v196, v93
	v_fmac_f32_e32 v62, v196, v94
	v_fmac_f32_e32 v63, v196, v95
	v_fmac_f32_e32 v48, v196, v88
	v_fmac_f32_e32 v49, v196, v89
	v_fmac_f32_e32 v50, v196, v90
	v_fmac_f32_e32 v51, v196, v91
	v_fmac_f32_e32 v52, v196, v92
	v_fmac_f32_e32 v53, v196, v93
	v_fmac_f32_e32 v54, v196, v94
	v_fmac_f32_e32 v55, v196, v95
	v_fmac_f32_e32 v40, v196, v88
	v_fmac_f32_e32 v41, v196, v89
	v_fmac_f32_e32 v42, v196, v90
	v_fmac_f32_e32 v43, v196, v91
	v_fmac_f32_e32 v44, v196, v92
	v_fmac_f32_e32 v45, v196, v93
	v_fmac_f32_e32 v46, v196, v94
	v_fmac_f32_e32 v47, v196, v95
	v_fmac_f32_e32 v32, v196, v88
	v_fmac_f32_e32 v33, v196, v89
	v_fmac_f32_e32 v34, v196, v90
	v_fmac_f32_e32 v35, v196, v91
	v_fmac_f32_e32 v36, v196, v92
	v_fmac_f32_e32 v37, v196, v93
	v_fmac_f32_e32 v38, v196, v94
	v_fmac_f32_e32 v39, v196, v95
	v_fmac_f32_e32 v24, v99, v88
	v_fmac_f32_e32 v25, v99, v89
	v_fmac_f32_e32 v26, v99, v90
	v_fmac_f32_e32 v27, v99, v91
	v_fmac_f32_e32 v28, v99, v92
	v_fmac_f32_e32 v29, v99, v93
	v_fmac_f32_e32 v30, v99, v94
	v_fmac_f32_e32 v31, v99, v95
	v_fmac_f32_e32 v16, v99, v88
	v_fmac_f32_e32 v17, v99, v89
	v_fmac_f32_e32 v18, v99, v90
	v_fmac_f32_e32 v19, v99, v91
	v_fmac_f32_e32 v20, v99, v92
	v_fmac_f32_e32 v21, v99, v93
	v_fmac_f32_e32 v22, v99, v94
	v_fmac_f32_e32 v23, v99, v95
	v_fmac_f32_e32 v8, v99, v88
	v_fmac_f32_e32 v9, v99, v89
	v_fmac_f32_e32 v10, v99, v90
	v_fmac_f32_e32 v11, v99, v91
	v_fmac_f32_e32 v12, v99, v92
	v_fmac_f32_e32 v13, v99, v93
	v_fmac_f32_e32 v14, v99, v94
	v_fmac_f32_e32 v15, v99, v95
	v_fmac_f32_e32 v0, v99, v88
	v_fmac_f32_e32 v1, v99, v89
	v_fmac_f32_e32 v2, v99, v90
	v_fmac_f32_e32 v3, v99, v91
	v_fmac_f32_e32 v4, v99, v92
	v_fmac_f32_e32 v5, v99, v93
	v_fmac_f32_e32 v6, v99, v94
	v_fmac_f32_e32 v7, v99, v95
	s_waitcnt vmcnt(10)
	v_lshlrev_b32_e32 v88, 16, v148
	v_and_b32_e32 v89, 0xffff0000, v148
	v_lshlrev_b32_e32 v90, 16, v149
	v_and_b32_e32 v91, 0xffff0000, v149
	v_lshlrev_b32_e32 v92, 16, v150
	v_and_b32_e32 v93, 0xffff0000, v150
	v_lshlrev_b32_e32 v94, 16, v151
	v_and_b32_e32 v95, 0xffff0000, v151
	v_fmac_f32_e32 v56, v196, v88
	v_fmac_f32_e32 v57, v196, v89
	v_fmac_f32_e32 v58, v196, v90
	v_fmac_f32_e32 v59, v196, v91
	v_fmac_f32_e32 v60, v196, v92
	v_fmac_f32_e32 v61, v196, v93
	v_fmac_f32_e32 v62, v196, v94
	v_fmac_f32_e32 v63, v196, v95
	v_fmac_f32_e32 v48, v196, v88
	v_fmac_f32_e32 v49, v196, v89
	v_fmac_f32_e32 v50, v196, v90
	v_fmac_f32_e32 v51, v196, v91
	v_fmac_f32_e32 v52, v196, v92
	v_fmac_f32_e32 v53, v196, v93
	v_fmac_f32_e32 v54, v196, v94
	v_fmac_f32_e32 v55, v196, v95
	v_fmac_f32_e32 v40, v196, v88
	v_fmac_f32_e32 v41, v196, v89
	v_fmac_f32_e32 v42, v196, v90
	v_fmac_f32_e32 v43, v196, v91
	v_fmac_f32_e32 v44, v196, v92
	v_fmac_f32_e32 v45, v196, v93
	v_fmac_f32_e32 v46, v196, v94
	v_fmac_f32_e32 v47, v196, v95
	v_fmac_f32_e32 v32, v196, v88
	v_fmac_f32_e32 v33, v196, v89
	v_fmac_f32_e32 v34, v196, v90
	v_fmac_f32_e32 v35, v196, v91
	v_fmac_f32_e32 v36, v196, v92
	v_fmac_f32_e32 v37, v196, v93
	v_fmac_f32_e32 v38, v196, v94
	v_fmac_f32_e32 v39, v196, v95
	v_fmac_f32_e32 v24, v196, v88
	v_fmac_f32_e32 v25, v196, v89
	v_fmac_f32_e32 v26, v196, v90
	v_fmac_f32_e32 v27, v196, v91
	v_fmac_f32_e32 v28, v196, v92
	v_fmac_f32_e32 v29, v196, v93
	v_fmac_f32_e32 v30, v196, v94
	v_fmac_f32_e32 v31, v196, v95
	v_fmac_f32_e32 v16, v99, v88
	v_fmac_f32_e32 v17, v99, v89
	v_fmac_f32_e32 v18, v99, v90
	v_fmac_f32_e32 v19, v99, v91
	v_fmac_f32_e32 v20, v99, v92
	v_fmac_f32_e32 v21, v99, v93
	v_fmac_f32_e32 v22, v99, v94
	v_fmac_f32_e32 v23, v99, v95
	v_fmac_f32_e32 v8, v99, v88
	v_fmac_f32_e32 v9, v99, v89
	v_fmac_f32_e32 v10, v99, v90
	v_fmac_f32_e32 v11, v99, v91
	v_fmac_f32_e32 v12, v99, v92
	v_fmac_f32_e32 v13, v99, v93
	v_fmac_f32_e32 v14, v99, v94
	v_fmac_f32_e32 v15, v99, v95
	v_fmac_f32_e32 v0, v99, v88
	v_fmac_f32_e32 v1, v99, v89
	v_fmac_f32_e32 v2, v99, v90
	v_fmac_f32_e32 v3, v99, v91
	v_fmac_f32_e32 v4, v99, v92
	v_fmac_f32_e32 v5, v99, v93
	v_fmac_f32_e32 v6, v99, v94
	v_fmac_f32_e32 v7, v99, v95
	s_waitcnt vmcnt(9)
	v_lshlrev_b32_e32 v88, 16, v152
	v_and_b32_e32 v89, 0xffff0000, v152
	v_lshlrev_b32_e32 v90, 16, v153
	v_and_b32_e32 v91, 0xffff0000, v153
	v_lshlrev_b32_e32 v92, 16, v154
	v_and_b32_e32 v93, 0xffff0000, v154
	v_lshlrev_b32_e32 v94, 16, v155
	v_and_b32_e32 v95, 0xffff0000, v155
	v_fmac_f32_e32 v56, v196, v88
	v_fmac_f32_e32 v57, v196, v89
	v_fmac_f32_e32 v58, v196, v90
	v_fmac_f32_e32 v59, v196, v91
	v_fmac_f32_e32 v60, v196, v92
	v_fmac_f32_e32 v61, v196, v93
	v_fmac_f32_e32 v62, v196, v94
	v_fmac_f32_e32 v63, v196, v95
	v_fmac_f32_e32 v48, v196, v88
	v_fmac_f32_e32 v49, v196, v89
	v_fmac_f32_e32 v50, v196, v90
	v_fmac_f32_e32 v51, v196, v91
	v_fmac_f32_e32 v52, v196, v92
	v_fmac_f32_e32 v53, v196, v93
	v_fmac_f32_e32 v54, v196, v94
	v_fmac_f32_e32 v55, v196, v95
	v_fmac_f32_e32 v40, v196, v88
	v_fmac_f32_e32 v41, v196, v89
	v_fmac_f32_e32 v42, v196, v90
	v_fmac_f32_e32 v43, v196, v91
	v_fmac_f32_e32 v44, v196, v92
	v_fmac_f32_e32 v45, v196, v93
	v_fmac_f32_e32 v46, v196, v94
	v_fmac_f32_e32 v47, v196, v95
	v_fmac_f32_e32 v32, v196, v88
	v_fmac_f32_e32 v33, v196, v89
	v_fmac_f32_e32 v34, v196, v90
	v_fmac_f32_e32 v35, v196, v91
	v_fmac_f32_e32 v36, v196, v92
	v_fmac_f32_e32 v37, v196, v93
	v_fmac_f32_e32 v38, v196, v94
	v_fmac_f32_e32 v39, v196, v95
	v_fmac_f32_e32 v24, v196, v88
	v_fmac_f32_e32 v25, v196, v89
	v_fmac_f32_e32 v26, v196, v90
	v_fmac_f32_e32 v27, v196, v91
	v_fmac_f32_e32 v28, v196, v92
	v_fmac_f32_e32 v29, v196, v93
	v_fmac_f32_e32 v30, v196, v94
	v_fmac_f32_e32 v31, v196, v95
	v_fmac_f32_e32 v16, v196, v88
	v_fmac_f32_e32 v17, v196, v89
	v_fmac_f32_e32 v18, v196, v90
	v_fmac_f32_e32 v19, v196, v91
	v_fmac_f32_e32 v20, v196, v92
	v_fmac_f32_e32 v21, v196, v93
	v_fmac_f32_e32 v22, v196, v94
	v_fmac_f32_e32 v23, v196, v95
	v_fmac_f32_e32 v8, v99, v88
	v_fmac_f32_e32 v9, v99, v89
	v_fmac_f32_e32 v10, v99, v90
	v_fmac_f32_e32 v11, v99, v91
	v_fmac_f32_e32 v12, v99, v92
	v_fmac_f32_e32 v13, v99, v93
	v_fmac_f32_e32 v14, v99, v94
	v_fmac_f32_e32 v15, v99, v95
	v_fmac_f32_e32 v0, v99, v88
	v_fmac_f32_e32 v1, v99, v89
	v_fmac_f32_e32 v2, v99, v90
	v_fmac_f32_e32 v3, v99, v91
	v_fmac_f32_e32 v4, v99, v92
	v_fmac_f32_e32 v5, v99, v93
	v_fmac_f32_e32 v6, v99, v94
	v_fmac_f32_e32 v7, v99, v95
	s_waitcnt vmcnt(8)
	v_lshlrev_b32_e32 v88, 16, v156
	v_and_b32_e32 v89, 0xffff0000, v156
	v_lshlrev_b32_e32 v90, 16, v157
	v_and_b32_e32 v91, 0xffff0000, v157
	v_lshlrev_b32_e32 v92, 16, v158
	v_and_b32_e32 v93, 0xffff0000, v158
	v_lshlrev_b32_e32 v94, 16, v159
	v_and_b32_e32 v95, 0xffff0000, v159
	v_fmac_f32_e32 v56, v196, v88
	v_fmac_f32_e32 v57, v196, v89
	v_fmac_f32_e32 v58, v196, v90
	v_fmac_f32_e32 v59, v196, v91
	v_fmac_f32_e32 v60, v196, v92
	v_fmac_f32_e32 v61, v196, v93
	v_fmac_f32_e32 v62, v196, v94
	v_fmac_f32_e32 v63, v196, v95
	v_fmac_f32_e32 v48, v196, v88
	v_fmac_f32_e32 v49, v196, v89
	v_fmac_f32_e32 v50, v196, v90
	v_fmac_f32_e32 v51, v196, v91
	v_fmac_f32_e32 v52, v196, v92
	v_fmac_f32_e32 v53, v196, v93
	v_fmac_f32_e32 v54, v196, v94
	v_fmac_f32_e32 v55, v196, v95
	v_fmac_f32_e32 v40, v196, v88
	v_fmac_f32_e32 v41, v196, v89
	v_fmac_f32_e32 v42, v196, v90
	v_fmac_f32_e32 v43, v196, v91
	v_fmac_f32_e32 v44, v196, v92
	v_fmac_f32_e32 v45, v196, v93
	v_fmac_f32_e32 v46, v196, v94
	v_fmac_f32_e32 v47, v196, v95
	v_fmac_f32_e32 v32, v196, v88
	v_fmac_f32_e32 v33, v196, v89
	v_fmac_f32_e32 v34, v196, v90
	v_fmac_f32_e32 v35, v196, v91
	v_fmac_f32_e32 v36, v196, v92
	v_fmac_f32_e32 v37, v196, v93
	v_fmac_f32_e32 v38, v196, v94
	v_fmac_f32_e32 v39, v196, v95
	v_fmac_f32_e32 v24, v196, v88
	v_fmac_f32_e32 v25, v196, v89
	v_fmac_f32_e32 v26, v196, v90
	v_fmac_f32_e32 v27, v196, v91
	v_fmac_f32_e32 v28, v196, v92
	v_fmac_f32_e32 v29, v196, v93
	v_fmac_f32_e32 v30, v196, v94
	v_fmac_f32_e32 v31, v196, v95
	v_fmac_f32_e32 v16, v196, v88
	v_fmac_f32_e32 v17, v196, v89
	v_fmac_f32_e32 v18, v196, v90
	v_fmac_f32_e32 v19, v196, v91
	v_fmac_f32_e32 v20, v196, v92
	v_fmac_f32_e32 v21, v196, v93
	v_fmac_f32_e32 v22, v196, v94
	v_fmac_f32_e32 v23, v196, v95
	v_fmac_f32_e32 v8, v196, v88
	v_fmac_f32_e32 v9, v196, v89
	v_fmac_f32_e32 v10, v196, v90
	v_fmac_f32_e32 v11, v196, v91
	v_fmac_f32_e32 v12, v196, v92
	v_fmac_f32_e32 v13, v196, v93
	v_fmac_f32_e32 v14, v196, v94
	v_fmac_f32_e32 v15, v196, v95
	v_fmac_f32_e32 v0, v99, v88
	v_fmac_f32_e32 v1, v99, v89
	v_fmac_f32_e32 v2, v99, v90
	v_fmac_f32_e32 v3, v99, v91
	v_fmac_f32_e32 v4, v99, v92
	v_fmac_f32_e32 v5, v99, v93
	v_fmac_f32_e32 v6, v99, v94
	v_fmac_f32_e32 v7, v99, v95
	s_waitcnt vmcnt(7)
	v_lshlrev_b32_e32 v88, 16, v160
	v_and_b32_e32 v89, 0xffff0000, v160
	v_lshlrev_b32_e32 v90, 16, v161
	v_and_b32_e32 v91, 0xffff0000, v161
	v_lshlrev_b32_e32 v92, 16, v162
	v_and_b32_e32 v93, 0xffff0000, v162
	v_lshlrev_b32_e32 v94, 16, v163
	v_and_b32_e32 v95, 0xffff0000, v163
	v_fmac_f32_e32 v56, v196, v88
	v_fmac_f32_e32 v57, v196, v89
	v_fmac_f32_e32 v58, v196, v90
	v_fmac_f32_e32 v59, v196, v91
	v_fmac_f32_e32 v60, v196, v92
	v_fmac_f32_e32 v61, v196, v93
	v_fmac_f32_e32 v62, v196, v94
	v_fmac_f32_e32 v63, v196, v95
	v_fmac_f32_e32 v48, v196, v88
	v_fmac_f32_e32 v49, v196, v89
	v_fmac_f32_e32 v50, v196, v90
	v_fmac_f32_e32 v51, v196, v91
	v_fmac_f32_e32 v52, v196, v92
	v_fmac_f32_e32 v53, v196, v93
	v_fmac_f32_e32 v54, v196, v94
	v_fmac_f32_e32 v55, v196, v95
	v_fmac_f32_e32 v40, v196, v88
	v_fmac_f32_e32 v41, v196, v89
	v_fmac_f32_e32 v42, v196, v90
	v_fmac_f32_e32 v43, v196, v91
	v_fmac_f32_e32 v44, v196, v92
	v_fmac_f32_e32 v45, v196, v93
	v_fmac_f32_e32 v46, v196, v94
	v_fmac_f32_e32 v47, v196, v95
	v_fmac_f32_e32 v32, v196, v88
	v_fmac_f32_e32 v33, v196, v89
	v_fmac_f32_e32 v34, v196, v90
	v_fmac_f32_e32 v35, v196, v91
	v_fmac_f32_e32 v36, v196, v92
	v_fmac_f32_e32 v37, v196, v93
	v_fmac_f32_e32 v38, v196, v94
	v_fmac_f32_e32 v39, v196, v95
	v_fmac_f32_e32 v24, v196, v88
	v_fmac_f32_e32 v25, v196, v89
	v_fmac_f32_e32 v26, v196, v90
	v_fmac_f32_e32 v27, v196, v91
	v_fmac_f32_e32 v28, v196, v92
	v_fmac_f32_e32 v29, v196, v93
	v_fmac_f32_e32 v30, v196, v94
	v_fmac_f32_e32 v31, v196, v95
	v_fmac_f32_e32 v16, v196, v88
	v_fmac_f32_e32 v17, v196, v89
	v_fmac_f32_e32 v18, v196, v90
	v_fmac_f32_e32 v19, v196, v91
	v_fmac_f32_e32 v20, v196, v92
	v_fmac_f32_e32 v21, v196, v93
	v_fmac_f32_e32 v22, v196, v94
	v_fmac_f32_e32 v23, v196, v95
	v_fmac_f32_e32 v8, v196, v88
	v_fmac_f32_e32 v9, v196, v89
	v_fmac_f32_e32 v10, v196, v90
	v_fmac_f32_e32 v11, v196, v91
	v_fmac_f32_e32 v12, v196, v92
	v_fmac_f32_e32 v13, v196, v93
	v_fmac_f32_e32 v14, v196, v94
	v_fmac_f32_e32 v15, v196, v95
	v_fmac_f32_e32 v0, v196, v88
	v_fmac_f32_e32 v1, v196, v89
	v_fmac_f32_e32 v2, v196, v90
	v_fmac_f32_e32 v3, v196, v91
	v_fmac_f32_e32 v4, v196, v92
	v_fmac_f32_e32 v5, v196, v93
	v_fmac_f32_e32 v6, v196, v94
	v_fmac_f32_e32 v7, v196, v95
	s_cmp_eq_u32 s12, 8
	s_cbranch_scc1 .LPS_ROWS_DONE
	s_waitcnt vmcnt(6)
	v_lshlrev_b32_e32 v88, 16, v164
	v_and_b32_e32 v89, 0xffff0000, v164
	v_lshlrev_b32_e32 v90, 16, v165
	v_and_b32_e32 v91, 0xffff0000, v165
	v_lshlrev_b32_e32 v92, 16, v166
	v_and_b32_e32 v93, 0xffff0000, v166
	v_lshlrev_b32_e32 v94, 16, v167
	v_and_b32_e32 v95, 0xffff0000, v167
	v_fmac_f32_e32 v48, v196, v88
	v_fmac_f32_e32 v49, v196, v89
	v_fmac_f32_e32 v50, v196, v90
	v_fmac_f32_e32 v51, v196, v91
	v_fmac_f32_e32 v52, v196, v92
	v_fmac_f32_e32 v53, v196, v93
	v_fmac_f32_e32 v54, v196, v94
	v_fmac_f32_e32 v55, v196, v95
	v_fmac_f32_e32 v40, v196, v88
	v_fmac_f32_e32 v41, v196, v89
	v_fmac_f32_e32 v42, v196, v90
	v_fmac_f32_e32 v43, v196, v91
	v_fmac_f32_e32 v44, v196, v92
	v_fmac_f32_e32 v45, v196, v93
	v_fmac_f32_e32 v46, v196, v94
	v_fmac_f32_e32 v47, v196, v95
	v_fmac_f32_e32 v32, v196, v88
	v_fmac_f32_e32 v33, v196, v89
	v_fmac_f32_e32 v34, v196, v90
	v_fmac_f32_e32 v35, v196, v91
	v_fmac_f32_e32 v36, v196, v92
	v_fmac_f32_e32 v37, v196, v93
	v_fmac_f32_e32 v38, v196, v94
	v_fmac_f32_e32 v39, v196, v95
	v_fmac_f32_e32 v24, v196, v88
	v_fmac_f32_e32 v25, v196, v89
	v_fmac_f32_e32 v26, v196, v90
	v_fmac_f32_e32 v27, v196, v91
	v_fmac_f32_e32 v28, v196, v92
	v_fmac_f32_e32 v29, v196, v93
	v_fmac_f32_e32 v30, v196, v94
	v_fmac_f32_e32 v31, v196, v95
	v_fmac_f32_e32 v16, v196, v88
	v_fmac_f32_e32 v17, v196, v89
	v_fmac_f32_e32 v18, v196, v90
	v_fmac_f32_e32 v19, v196, v91
	v_fmac_f32_e32 v20, v196, v92
	v_fmac_f32_e32 v21, v196, v93
	v_fmac_f32_e32 v22, v196, v94
	v_fmac_f32_e32 v23, v196, v95
	v_fmac_f32_e32 v8, v196, v88
	v_fmac_f32_e32 v9, v196, v89
	v_fmac_f32_e32 v10, v196, v90
	v_fmac_f32_e32 v11, v196, v91
	v_fmac_f32_e32 v12, v196, v92
	v_fmac_f32_e32 v13, v196, v93
	v_fmac_f32_e32 v14, v196, v94
	v_fmac_f32_e32 v15, v196, v95
	v_fmac_f32_e32 v0, v196, v88
	v_fmac_f32_e32 v1, v196, v89
	v_fmac_f32_e32 v2, v196, v90
	v_fmac_f32_e32 v3, v196, v91
	v_fmac_f32_e32 v4, v196, v92
	v_fmac_f32_e32 v5, v196, v93
	v_fmac_f32_e32 v6, v196, v94
	v_fmac_f32_e32 v7, v196, v95
	s_waitcnt vmcnt(5)
	v_lshlrev_b32_e32 v88, 16, v168
	v_and_b32_e32 v89, 0xffff0000, v168
	v_lshlrev_b32_e32 v90, 16, v169
	v_and_b32_e32 v91, 0xffff0000, v169
	v_lshlrev_b32_e32 v92, 16, v170
	v_and_b32_e32 v93, 0xffff0000, v170
	v_lshlrev_b32_e32 v94, 16, v171
	v_and_b32_e32 v95, 0xffff0000, v171
	v_fmac_f32_e32 v40, v196, v88
	v_fmac_f32_e32 v41, v196, v89
	v_fmac_f32_e32 v42, v196, v90
	v_fmac_f32_e32 v43, v196, v91
	v_fmac_f32_e32 v44, v196, v92
	v_fmac_f32_e32 v45, v196, v93
	v_fmac_f32_e32 v46, v196, v94
	v_fmac_f32_e32 v47, v196, v95
	v_fmac_f32_e32 v32, v196, v88
	v_fmac_f32_e32 v33, v196, v89
	v_fmac_f32_e32 v34, v196, v90
	v_fmac_f32_e32 v35, v196, v91
	v_fmac_f32_e32 v36, v196, v92
	v_fmac_f32_e32 v37, v196, v93
	v_fmac_f32_e32 v38, v196, v94
	v_fmac_f32_e32 v39, v196, v95
	v_fmac_f32_e32 v24, v196, v88
	v_fmac_f32_e32 v25, v196, v89
	v_fmac_f32_e32 v26, v196, v90
	v_fmac_f32_e32 v27, v196, v91
	v_fmac_f32_e32 v28, v196, v92
	v_fmac_f32_e32 v29, v196, v93
	v_fmac_f32_e32 v30, v196, v94
	v_fmac_f32_e32 v31, v196, v95
	v_fmac_f32_e32 v16, v196, v88
	v_fmac_f32_e32 v17, v196, v89
	v_fmac_f32_e32 v18, v196, v90
	v_fmac_f32_e32 v19, v196, v91
	v_fmac_f32_e32 v20, v196, v92
	v_fmac_f32_e32 v21, v196, v93
	v_fmac_f32_e32 v22, v196, v94
	v_fmac_f32_e32 v23, v196, v95
	v_fmac_f32_e32 v8, v196, v88
	v_fmac_f32_e32 v9, v196, v89
	v_fmac_f32_e32 v10, v196, v90
	v_fmac_f32_e32 v11, v196, v91
	v_fmac_f32_e32 v12, v196, v92
	v_fmac_f32_e32 v13, v196, v93
	v_fmac_f32_e32 v14, v196, v94
	v_fmac_f32_e32 v15, v196, v95
	v_fmac_f32_e32 v0, v196, v88
	v_fmac_f32_e32 v1, v196, v89
	v_fmac_f32_e32 v2, v196, v90
	v_fmac_f32_e32 v3, v196, v91
	v_fmac_f32_e32 v4, v196, v92
	v_fmac_f32_e32 v5, v196, v93
	v_fmac_f32_e32 v6, v196, v94
	v_fmac_f32_e32 v7, v196, v95
	s_waitcnt vmcnt(4)
	v_lshlrev_b32_e32 v88, 16, v172
	v_and_b32_e32 v89, 0xffff0000, v172
	v_lshlrev_b32_e32 v90, 16, v173
	v_and_b32_e32 v91, 0xffff0000, v173
	v_lshlrev_b32_e32 v92, 16, v174
	v_and_b32_e32 v93, 0xffff0000, v174
	v_lshlrev_b32_e32 v94, 16, v175
	v_and_b32_e32 v95, 0xffff0000, v175
	v_fmac_f32_e32 v32, v196, v88
	v_fmac_f32_e32 v33, v196, v89
	v_fmac_f32_e32 v34, v196, v90
	v_fmac_f32_e32 v35, v196, v91
	v_fmac_f32_e32 v36, v196, v92
	v_fmac_f32_e32 v37, v196, v93
	v_fmac_f32_e32 v38, v196, v94
	v_fmac_f32_e32 v39, v196, v95
	v_fmac_f32_e32 v24, v196, v88
	v_fmac_f32_e32 v25, v196, v89
	v_fmac_f32_e32 v26, v196, v90
	v_fmac_f32_e32 v27, v196, v91
	v_fmac_f32_e32 v28, v196, v92
	v_fmac_f32_e32 v29, v196, v93
	v_fmac_f32_e32 v30, v196, v94
	v_fmac_f32_e32 v31, v196, v95
	v_fmac_f32_e32 v16, v196, v88
	v_fmac_f32_e32 v17, v196, v89
	v_fmac_f32_e32 v18, v196, v90
	v_fmac_f32_e32 v19, v196, v91
	v_fmac_f32_e32 v20, v196, v92
	v_fmac_f32_e32 v21, v196, v93
	v_fmac_f32_e32 v22, v196, v94
	v_fmac_f32_e32 v23, v196, v95
	v_fmac_f32_e32 v8, v196, v88
	v_fmac_f32_e32 v9, v196, v89
	v_fmac_f32_e32 v10, v196, v90
	v_fmac_f32_e32 v11, v196, v91
	v_fmac_f32_e32 v12, v196, v92
	v_fmac_f32_e32 v13, v196, v93
	v_fmac_f32_e32 v14, v196, v94
	v_fmac_f32_e32 v15, v196, v95
	v_fmac_f32_e32 v0, v196, v88
	v_fmac_f32_e32 v1, v196, v89
	v_fmac_f32_e32 v2, v196, v90
	v_fmac_f32_e32 v3, v196, v91
	v_fmac_f32_e32 v4, v196, v92
	v_fmac_f32_e32 v5, v196, v93
	v_fmac_f32_e32 v6, v196, v94
	v_fmac_f32_e32 v7, v196, v95
	s_waitcnt vmcnt(3)
	v_lshlrev_b32_e32 v88, 16, v176
	v_and_b32_e32 v89, 0xffff0000, v176
	v_lshlrev_b32_e32 v90, 16, v177
	v_and_b32_e32 v91, 0xffff0000, v177
	v_lshlrev_b32_e32 v92, 16, v178
	v_and_b32_e32 v93, 0xffff0000, v178
	v_lshlrev_b32_e32 v94, 16, v179
	v_and_b32_e32 v95, 0xffff0000, v179
	v_fmac_f32_e32 v24, v196, v88
	v_fmac_f32_e32 v25, v196, v89
	v_fmac_f32_e32 v26, v196, v90
	v_fmac_f32_e32 v27, v196, v91
	v_fmac_f32_e32 v28, v196, v92
	v_fmac_f32_e32 v29, v196, v93
	v_fmac_f32_e32 v30, v196, v94
	v_fmac_f32_e32 v31, v196, v95
	v_fmac_f32_e32 v16, v196, v88
	v_fmac_f32_e32 v17, v196, v89
	v_fmac_f32_e32 v18, v196, v90
	v_fmac_f32_e32 v19, v196, v91
	v_fmac_f32_e32 v20, v196, v92
	v_fmac_f32_e32 v21, v196, v93
	v_fmac_f32_e32 v22, v196, v94
	v_fmac_f32_e32 v23, v196, v95
	v_fmac_f32_e32 v8, v196, v88
	v_fmac_f32_e32 v9, v196, v89
	v_fmac_f32_e32 v10, v196, v90
	v_fmac_f32_e32 v11, v196, v91
	v_fmac_f32_e32 v12, v196, v92
	v_fmac_f32_e32 v13, v196, v93
	v_fmac_f32_e32 v14, v196, v94
	v_fmac_f32_e32 v15, v196, v95
	v_fmac_f32_e32 v0, v196, v88
	v_fmac_f32_e32 v1, v196, v89
	v_fmac_f32_e32 v2, v196, v90
	v_fmac_f32_e32 v3, v196, v91
	v_fmac_f32_e32 v4, v196, v92
	v_fmac_f32_e32 v5, v196, v93
	v_fmac_f32_e32 v6, v196, v94
	v_fmac_f32_e32 v7, v196, v95
	s_waitcnt vmcnt(2)
	v_lshlrev_b32_e32 v88, 16, v180
	v_and_b32_e32 v89, 0xffff0000, v180
	v_lshlrev_b32_e32 v90, 16, v181
	v_and_b32_e32 v91, 0xffff0000, v181
	v_lshlrev_b32_e32 v92, 16, v182
	v_and_b32_e32 v93, 0xffff0000, v182
	v_lshlrev_b32_e32 v94, 16, v183
	v_and_b32_e32 v95, 0xffff0000, v183
	v_fmac_f32_e32 v16, v196, v88
	v_fmac_f32_e32 v17, v196, v89
	v_fmac_f32_e32 v18, v196, v90
	v_fmac_f32_e32 v19, v196, v91
	v_fmac_f32_e32 v20, v196, v92
	v_fmac_f32_e32 v21, v196, v93
	v_fmac_f32_e32 v22, v196, v94
	v_fmac_f32_e32 v23, v196, v95
	v_fmac_f32_e32 v8, v196, v88
	v_fmac_f32_e32 v9, v196, v89
	v_fmac_f32_e32 v10, v196, v90
	v_fmac_f32_e32 v11, v196, v91
	v_fmac_f32_e32 v12, v196, v92
	v_fmac_f32_e32 v13, v196, v93
	v_fmac_f32_e32 v14, v196, v94
	v_fmac_f32_e32 v15, v196, v95
	v_fmac_f32_e32 v0, v196, v88
	v_fmac_f32_e32 v1, v196, v89
	v_fmac_f32_e32 v2, v196, v90
	v_fmac_f32_e32 v3, v196, v91
	v_fmac_f32_e32 v4, v196, v92
	v_fmac_f32_e32 v5, v196, v93
	v_fmac_f32_e32 v6, v196, v94
	v_fmac_f32_e32 v7, v196, v95
	s_waitcnt vmcnt(1)
	v_lshlrev_b32_e32 v88, 16, v184
	v_and_b32_e32 v89, 0xffff0000, v184
	v_lshlrev_b32_e32 v90, 16, v185
	v_and_b32_e32 v91, 0xffff0000, v185
	v_lshlrev_b32_e32 v92, 16, v186
	v_and_b32_e32 v93, 0xffff0000, v186
	v_lshlrev_b32_e32 v94, 16, v187
	v_and_b32_e32 v95, 0xffff0000, v187
	v_fmac_f32_e32 v8, v196, v88
	v_fmac_f32_e32 v9, v196, v89
	v_fmac_f32_e32 v10, v196, v90
	v_fmac_f32_e32 v11, v196, v91
	v_fmac_f32_e32 v12, v196, v92
	v_fmac_f32_e32 v13, v196, v93
	v_fmac_f32_e32 v14, v196, v94
	v_fmac_f32_e32 v15, v196, v95
	v_fmac_f32_e32 v0, v196, v88
	v_fmac_f32_e32 v1, v196, v89
	v_fmac_f32_e32 v2, v196, v90
	v_fmac_f32_e32 v3, v196, v91
	v_fmac_f32_e32 v4, v196, v92
	v_fmac_f32_e32 v5, v196, v93
	v_fmac_f32_e32 v6, v196, v94
	v_fmac_f32_e32 v7, v196, v95
	s_waitcnt vmcnt(0)
	v_lshlrev_b32_e32 v88, 16, v188
	v_and_b32_e32 v89, 0xffff0000, v188
	v_lshlrev_b32_e32 v90, 16, v189
	v_and_b32_e32 v91, 0xffff0000, v189
	v_lshlrev_b32_e32 v92, 16, v190
	v_and_b32_e32 v93, 0xffff0000, v190
	v_lshlrev_b32_e32 v94, 16, v191
	v_and_b32_e32 v95, 0xffff0000, v191
	v_fmac_f32_e32 v0, v196, v88
	v_fmac_f32_e32 v1, v196, v89
	v_fmac_f32_e32 v2, v196, v90
	v_fmac_f32_e32 v3, v196, v91
	v_fmac_f32_e32 v4, v196, v92
	v_fmac_f32_e32 v5, v196, v93
	v_fmac_f32_e32 v6, v196, v94
	v_fmac_f32_e32 v7, v196, v95
.LPS_ROWS_DONE:
	s_waitcnt vmcnt(0)
	s_lshl_b32 s13, s12, 11
	s_add_u32 s14, s10, s13
	s_addc_u32 s15, s11, 0
	s_add_u32 s14, s14, 0x13a00000
	s_addc_u32 s15, s15, 0

	s_cmp_lt_u32 s12, 16
	s_cbranch_scc0 .LPS_IC0
	s_add_i32 s13, s12, 1
	v_min_i32_e32 v81, s13, v195
	v_cvt_f32_i32_e32 v81, v81
	v_div_scale_f32 v82, s[26:27], v81, v81, 1.0
	v_rcp_f32_e32 v85, v82
	s_nop 0
	v_fma_f32 v83, -v82, v85, 1.0
	v_fmac_f32_e32 v85, v83, v85
	v_div_scale_f32 v83, vcc, 1.0, v81, 1.0
	v_mul_f32_e32 v86, v83, v85
	v_fma_f32 v84, -v82, v86, v83
	v_fmac_f32_e32 v86, v84, v85
	v_fma_f32 v83, -v82, v86, v83
	v_div_fmas_f32 v83, v83, v85, v86
	v_div_fixup_f32 v80, v83, v81, 1.0

.LPS_IC0:
	v_lshlrev_b32_e32 v88, 16, v128
	v_and_b32_e32 v89, 0xffff0000, v128
	v_lshlrev_b32_e32 v90, 16, v129
	v_and_b32_e32 v91, 0xffff0000, v129
	v_lshlrev_b32_e32 v92, 16, v130
	v_and_b32_e32 v93, 0xffff0000, v130
	v_lshlrev_b32_e32 v94, 16, v131
	v_and_b32_e32 v95, 0xffff0000, v131
	v_fma_f32 v0, v80, v0, -v88
	v_fma_f32 v1, v80, v1, -v89
	v_fma_f32 v2, v80, v2, -v90
	v_fma_f32 v3, v80, v3, -v91
	v_fma_f32 v4, v80, v4, -v92
	v_fma_f32 v5, v80, v5, -v93
	v_fma_f32 v6, v80, v6, -v94
	v_fma_f32 v7, v80, v7, -v95
	v_cvt_pk_bf16_f32 v0, v0, v1
	v_cvt_pk_bf16_f32 v1, v2, v3
	v_cvt_pk_bf16_f32 v2, v4, v5
	v_cvt_pk_bf16_f32 v3, v6, v7
	global_store_dwordx4 v192, v[0:3], s[14:15]
	s_cmp_lt_u32 s12, 16
	s_cbranch_scc0 .LPS_IC1
	s_add_i32 s13, s12, 2
	v_min_i32_e32 v81, s13, v195
	v_cvt_f32_i32_e32 v81, v81
	v_div_scale_f32 v82, s[26:27], v81, v81, 1.0
	v_rcp_f32_e32 v85, v82
	s_nop 0
	v_fma_f32 v83, -v82, v85, 1.0
	v_fmac_f32_e32 v85, v83, v85
	v_div_scale_f32 v83, vcc, 1.0, v81, 1.0
	v_mul_f32_e32 v86, v83, v85
	v_fma_f32 v84, -v82, v86, v83
	v_fmac_f32_e32 v86, v84, v85
	v_fma_f32 v83, -v82, v86, v83
	v_div_fmas_f32 v83, v83, v85, v86
	v_div_fixup_f32 v80, v83, v81, 1.0

.LPS_IC1:
	v_lshlrev_b32_e32 v88, 16, v124
	v_and_b32_e32 v89, 0xffff0000, v124
	v_lshlrev_b32_e32 v90, 16, v125
	v_and_b32_e32 v91, 0xffff0000, v125
	v_lshlrev_b32_e32 v92, 16, v126
	v_and_b32_e32 v93, 0xffff0000, v126
	v_lshlrev_b32_e32 v94, 16, v127
	v_and_b32_e32 v95, 0xffff0000, v127
	v_fma_f32 v8, v80, v8, -v88
	v_fma_f32 v9, v80, v9, -v89
	v_fma_f32 v10, v80, v10, -v90
	v_fma_f32 v11, v80, v11, -v91
	v_fma_f32 v12, v80, v12, -v92
	v_fma_f32 v13, v80, v13, -v93
	v_fma_f32 v14, v80, v14, -v94
	v_fma_f32 v15, v80, v15, -v95
	v_cvt_pk_bf16_f32 v8, v8, v9
	v_cvt_pk_bf16_f32 v9, v10, v11
	v_cvt_pk_bf16_f32 v10, v12, v13
	v_cvt_pk_bf16_f32 v11, v14, v15
	s_add_u32 s14, s14, 0x800
	s_addc_u32 s15, s15, 0
	global_store_dwordx4 v192, v[8:11], s[14:15]
	s_cmp_lt_u32 s12, 16
	s_cbranch_scc0 .LPS_IC2
	s_add_i32 s13, s12, 3
	v_min_i32_e32 v81, s13, v195
	v_cvt_f32_i32_e32 v81, v81
	v_div_scale_f32 v82, s[26:27], v81, v81, 1.0
	v_rcp_f32_e32 v85, v82
	s_nop 0
	v_fma_f32 v83, -v82, v85, 1.0
	v_fmac_f32_e32 v85, v83, v85
	v_div_scale_f32 v83, vcc, 1.0, v81, 1.0
	v_mul_f32_e32 v86, v83, v85
	v_fma_f32 v84, -v82, v86, v83
	v_fmac_f32_e32 v86, v84, v85
	v_fma_f32 v83, -v82, v86, v83
	v_div_fmas_f32 v83, v83, v85, v86
	v_div_fixup_f32 v80, v83, v81, 1.0

.LPS_IC2:
	v_lshlrev_b32_e32 v88, 16, v120
	v_and_b32_e32 v89, 0xffff0000, v120
	v_lshlrev_b32_e32 v90, 16, v121
	v_and_b32_e32 v91, 0xffff0000, v121
	v_lshlrev_b32_e32 v92, 16, v122
	v_and_b32_e32 v93, 0xffff0000, v122
	v_lshlrev_b32_e32 v94, 16, v123
	v_and_b32_e32 v95, 0xffff0000, v123
	v_fma_f32 v16, v80, v16, -v88
	v_fma_f32 v17, v80, v17, -v89
	v_fma_f32 v18, v80, v18, -v90
	v_fma_f32 v19, v80, v19, -v91
	v_fma_f32 v20, v80, v20, -v92
	v_fma_f32 v21, v80, v21, -v93
	v_fma_f32 v22, v80, v22, -v94
	v_fma_f32 v23, v80, v23, -v95
	v_cvt_pk_bf16_f32 v16, v16, v17
	v_cvt_pk_bf16_f32 v17, v18, v19
	v_cvt_pk_bf16_f32 v18, v20, v21
	v_cvt_pk_bf16_f32 v19, v22, v23
	s_add_u32 s14, s14, 0x800
	s_addc_u32 s15, s15, 0
	global_store_dwordx4 v192, v[16:19], s[14:15]
	s_cmp_lt_u32 s12, 16
	s_cbranch_scc0 .LPS_IC3
	s_add_i32 s13, s12, 4
	v_min_i32_e32 v81, s13, v195
	v_cvt_f32_i32_e32 v81, v81
	v_div_scale_f32 v82, s[26:27], v81, v81, 1.0
	v_rcp_f32_e32 v85, v82
	s_nop 0
	v_fma_f32 v83, -v82, v85, 1.0
	v_fmac_f32_e32 v85, v83, v85
	v_div_scale_f32 v83, vcc, 1.0, v81, 1.0
	v_mul_f32_e32 v86, v83, v85
	v_fma_f32 v84, -v82, v86, v83
	v_fmac_f32_e32 v86, v84, v85
	v_fma_f32 v83, -v82, v86, v83
	v_div_fmas_f32 v83, v83, v85, v86
	v_div_fixup_f32 v80, v83, v81, 1.0

.LPS_IC3:
	v_lshlrev_b32_e32 v88, 16, v116
	v_and_b32_e32 v89, 0xffff0000, v116
	v_lshlrev_b32_e32 v90, 16, v117
	v_and_b32_e32 v91, 0xffff0000, v117
	v_lshlrev_b32_e32 v92, 16, v118
	v_and_b32_e32 v93, 0xffff0000, v118
	v_lshlrev_b32_e32 v94, 16, v119
	v_and_b32_e32 v95, 0xffff0000, v119
	v_fma_f32 v24, v80, v24, -v88
	v_fma_f32 v25, v80, v25, -v89
	v_fma_f32 v26, v80, v26, -v90
	v_fma_f32 v27, v80, v27, -v91
	v_fma_f32 v28, v80, v28, -v92
	v_fma_f32 v29, v80, v29, -v93
	v_fma_f32 v30, v80, v30, -v94
	v_fma_f32 v31, v80, v31, -v95
	v_cvt_pk_bf16_f32 v24, v24, v25
	v_cvt_pk_bf16_f32 v25, v26, v27
	v_cvt_pk_bf16_f32 v26, v28, v29
	v_cvt_pk_bf16_f32 v27, v30, v31
	s_add_u32 s14, s14, 0x800
	s_addc_u32 s15, s15, 0
	global_store_dwordx4 v192, v[24:27], s[14:15]
	s_cmp_lt_u32 s12, 16
	s_cbranch_scc0 .LPS_IC4
	s_add_i32 s13, s12, 5
	v_min_i32_e32 v81, s13, v195
	v_cvt_f32_i32_e32 v81, v81
	v_div_scale_f32 v82, s[26:27], v81, v81, 1.0
	v_rcp_f32_e32 v85, v82
	s_nop 0
	v_fma_f32 v83, -v82, v85, 1.0
	v_fmac_f32_e32 v85, v83, v85
	v_div_scale_f32 v83, vcc, 1.0, v81, 1.0
	v_mul_f32_e32 v86, v83, v85
	v_fma_f32 v84, -v82, v86, v83
	v_fmac_f32_e32 v86, v84, v85
	v_fma_f32 v83, -v82, v86, v83
	v_div_fmas_f32 v83, v83, v85, v86
	v_div_fixup_f32 v80, v83, v81, 1.0

.LPS_IC4:
	v_lshlrev_b32_e32 v88, 16, v112
	v_and_b32_e32 v89, 0xffff0000, v112
	v_lshlrev_b32_e32 v90, 16, v113
	v_and_b32_e32 v91, 0xffff0000, v113
	v_lshlrev_b32_e32 v92, 16, v114
	v_and_b32_e32 v93, 0xffff0000, v114
	v_lshlrev_b32_e32 v94, 16, v115
	v_and_b32_e32 v95, 0xffff0000, v115
	v_fma_f32 v32, v80, v32, -v88
	v_fma_f32 v33, v80, v33, -v89
	v_fma_f32 v34, v80, v34, -v90
	v_fma_f32 v35, v80, v35, -v91
	v_fma_f32 v36, v80, v36, -v92
	v_fma_f32 v37, v80, v37, -v93
	v_fma_f32 v38, v80, v38, -v94
	v_fma_f32 v39, v80, v39, -v95
	v_cvt_pk_bf16_f32 v32, v32, v33
	v_cvt_pk_bf16_f32 v33, v34, v35
	v_cvt_pk_bf16_f32 v34, v36, v37
	v_cvt_pk_bf16_f32 v35, v38, v39
	s_add_u32 s14, s14, 0x800
	s_addc_u32 s15, s15, 0
	global_store_dwordx4 v192, v[32:35], s[14:15]
	s_cmp_lt_u32 s12, 16
	s_cbranch_scc0 .LPS_IC5
	s_add_i32 s13, s12, 6
	v_min_i32_e32 v81, s13, v195
	v_cvt_f32_i32_e32 v81, v81
	v_div_scale_f32 v82, s[26:27], v81, v81, 1.0
	v_rcp_f32_e32 v85, v82
	s_nop 0
	v_fma_f32 v83, -v82, v85, 1.0
	v_fmac_f32_e32 v85, v83, v85
	v_div_scale_f32 v83, vcc, 1.0, v81, 1.0
	v_mul_f32_e32 v86, v83, v85
	v_fma_f32 v84, -v82, v86, v83
	v_fmac_f32_e32 v86, v84, v85
	v_fma_f32 v83, -v82, v86, v83
	v_div_fmas_f32 v83, v83, v85, v86
	v_div_fixup_f32 v80, v83, v81, 1.0

.LPS_IC5:
	v_lshlrev_b32_e32 v88, 16, v108
	v_and_b32_e32 v89, 0xffff0000, v108
	v_lshlrev_b32_e32 v90, 16, v109
	v_and_b32_e32 v91, 0xffff0000, v109
	v_lshlrev_b32_e32 v92, 16, v110
	v_and_b32_e32 v93, 0xffff0000, v110
	v_lshlrev_b32_e32 v94, 16, v111
	v_and_b32_e32 v95, 0xffff0000, v111
	v_fma_f32 v40, v80, v40, -v88
	v_fma_f32 v41, v80, v41, -v89
	v_fma_f32 v42, v80, v42, -v90
	v_fma_f32 v43, v80, v43, -v91
	v_fma_f32 v44, v80, v44, -v92
	v_fma_f32 v45, v80, v45, -v93
	v_fma_f32 v46, v80, v46, -v94
	v_fma_f32 v47, v80, v47, -v95
	v_cvt_pk_bf16_f32 v40, v40, v41
	v_cvt_pk_bf16_f32 v41, v42, v43
	v_cvt_pk_bf16_f32 v42, v44, v45
	v_cvt_pk_bf16_f32 v43, v46, v47
	s_add_u32 s14, s14, 0x800
	s_addc_u32 s15, s15, 0
	global_store_dwordx4 v192, v[40:43], s[14:15]
	s_cmp_lt_u32 s12, 16
	s_cbranch_scc0 .LPS_IC6
	s_add_i32 s13, s12, 7
	v_min_i32_e32 v81, s13, v195
	v_cvt_f32_i32_e32 v81, v81
	v_div_scale_f32 v82, s[26:27], v81, v81, 1.0
	v_rcp_f32_e32 v85, v82
	s_nop 0
	v_fma_f32 v83, -v82, v85, 1.0
	v_fmac_f32_e32 v85, v83, v85
	v_div_scale_f32 v83, vcc, 1.0, v81, 1.0
	v_mul_f32_e32 v86, v83, v85
	v_fma_f32 v84, -v82, v86, v83
	v_fmac_f32_e32 v86, v84, v85
	v_fma_f32 v83, -v82, v86, v83
	v_div_fmas_f32 v83, v83, v85, v86
	v_div_fixup_f32 v80, v83, v81, 1.0

.LPS_IC6:
	v_lshlrev_b32_e32 v88, 16, v104
	v_and_b32_e32 v89, 0xffff0000, v104
	v_lshlrev_b32_e32 v90, 16, v105
	v_and_b32_e32 v91, 0xffff0000, v105
	v_lshlrev_b32_e32 v92, 16, v106
	v_and_b32_e32 v93, 0xffff0000, v106
	v_lshlrev_b32_e32 v94, 16, v107
	v_and_b32_e32 v95, 0xffff0000, v107
	v_fma_f32 v48, v80, v48, -v88
	v_fma_f32 v49, v80, v49, -v89
	v_fma_f32 v50, v80, v50, -v90
	v_fma_f32 v51, v80, v51, -v91
	v_fma_f32 v52, v80, v52, -v92
	v_fma_f32 v53, v80, v53, -v93
	v_fma_f32 v54, v80, v54, -v94
	v_fma_f32 v55, v80, v55, -v95
	v_cvt_pk_bf16_f32 v48, v48, v49
	v_cvt_pk_bf16_f32 v49, v50, v51
	v_cvt_pk_bf16_f32 v50, v52, v53
	v_cvt_pk_bf16_f32 v51, v54, v55
	s_add_u32 s14, s14, 0x800
	s_addc_u32 s15, s15, 0
	global_store_dwordx4 v192, v[48:51], s[14:15]
	s_cmp_lt_u32 s12, 16
	s_cbranch_scc0 .LPS_IC7
	s_add_i32 s13, s12, 8
	v_min_i32_e32 v81, s13, v195
	v_cvt_f32_i32_e32 v81, v81
	v_div_scale_f32 v82, s[26:27], v81, v81, 1.0
	v_rcp_f32_e32 v85, v82
	s_nop 0
	v_fma_f32 v83, -v82, v85, 1.0
	v_fmac_f32_e32 v85, v83, v85
	v_div_scale_f32 v83, vcc, 1.0, v81, 1.0
	v_mul_f32_e32 v86, v83, v85
	v_fma_f32 v84, -v82, v86, v83
	v_fmac_f32_e32 v86, v84, v85
	v_fma_f32 v83, -v82, v86, v83
	v_div_fmas_f32 v83, v83, v85, v86
	v_div_fixup_f32 v80, v83, v81, 1.0

.LPS_IC7:
	v_lshlrev_b32_e32 v88, 16, v100
	v_and_b32_e32 v89, 0xffff0000, v100
	v_lshlrev_b32_e32 v90, 16, v101
	v_and_b32_e32 v91, 0xffff0000, v101
	v_lshlrev_b32_e32 v92, 16, v102
	v_and_b32_e32 v93, 0xffff0000, v102
	v_lshlrev_b32_e32 v94, 16, v103
	v_and_b32_e32 v95, 0xffff0000, v103
	v_fma_f32 v56, v80, v56, -v88
	v_fma_f32 v57, v80, v57, -v89
	v_fma_f32 v58, v80, v58, -v90
	v_fma_f32 v59, v80, v59, -v91
	v_fma_f32 v60, v80, v60, -v92
	v_fma_f32 v61, v80, v61, -v93
	v_fma_f32 v62, v80, v62, -v94
	v_fma_f32 v63, v80, v63, -v95
	v_cvt_pk_bf16_f32 v56, v56, v57
	v_cvt_pk_bf16_f32 v57, v58, v59
	v_cvt_pk_bf16_f32 v58, v60, v61
	v_cvt_pk_bf16_f32 v59, v62, v63
	s_add_u32 s14, s14, 0x800
	s_addc_u32 s15, s15, 0
	global_store_dwordx4 v192, v[56:59], s[14:15]
	s_lshl_b32 s13, s12, 3
	s_add_u32 s14, s10, s13
	s_addc_u32 s15, s11, 0
	s_add_u32 s14, s14, 0x100000
	s_addc_u32 s15, s15, 0
	s_mov_b64 s[16:17], exec
	s_mov_b32 exec_lo, 0
	s_brev_b32 exec_hi, 1
	global_store_dwordx4 v97, v[64:67], s[14:15]
	global_store_dwordx4 v97, v[68:71], s[14:15] offset:16
	global_store_dwordx4 v97, v[72:75], s[14:15] offset:32
	global_store_dwordx4 v97, v[76:79], s[14:15] offset:48
	s_mov_b64 exec, s[16:17]
	s_add_i32 s24, s24, s21
	s_cmpk_lt_i32 s24, 0x800
	s_cbranch_scc1 .LPS_LOOP

